# leading half takes the epilogue-alignment barrier after its epilogue loads+cvts instead of before the epilogue (P2,P3,P5,P11,P13); on top of v2
# speedup vs baseline: 1.0018x; 1.0018x over previous
.LBB0_216:
	v_lshl_or_b32 v172, s92, 7, v155
	v_ashrrev_i32_e32 v173, 31, v172
	v_lshlrev_b64 v[146:147], 2, v[172:173]
	v_lshl_add_u64 v[152:153], s[80:81], 0, v[146:147]
	v_lshl_add_u64 v[146:147], s[36:37], 0, v[146:147]
	global_load_dwordx4 v[148:151], v[152:153], off
	global_load_dwordx4 v[160:163], v[152:153], off offset:16
	global_load_dwordx4 v[164:167], v[146:147], off
	global_load_dwordx4 v[168:171], v[146:147], off offset:16
	v_lshl_add_u32 v146, s82, 8, v1
	v_ashrrev_i32_e32 v147, 31, v146
	v_lshl_add_u64 v[152:153], v[146:147], 2, s[70:71]
	global_load_dword v174, v[152:153], off
	global_load_dword v192, v[152:153], off offset:64
	global_load_dword v193, v[152:153], off offset:128
	global_load_dword v194, v[152:153], off offset:192
	global_load_dword v195, v[152:153], off offset:512
	global_load_dword v196, v[152:153], off offset:576
	global_load_dword v197, v[152:153], off offset:640
	global_load_dword v198, v[152:153], off offset:704
	v_cvt_f32_i32_e32 v177, v127
	v_cvt_f32_i32_e32 v176, v126
	v_cvt_f32_i32_e32 v185, v119
	v_cvt_f32_i32_e32 v184, v118
	v_cvt_f32_i32_e32 v179, v129
	v_cvt_f32_i32_e32 v178, v128
	v_cvt_f32_i32_e32 v187, v121
	v_cvt_f32_i32_e32 v186, v120
	v_cvt_f32_i32_e32 v189, v115
	v_cvt_f32_i32_e32 v188, v114
	v_mov_b64_e32 v[114:115], s[38:39]
	v_cvt_f32_i32_e32 v191, v117
	v_cvt_f32_i32_e32 v190, v116
	v_mad_i64_i32 v[118:119], s[8:9], v146, s91, v[114:115]
	v_lshlrev_b64 v[116:117], 1, v[172:173]
	v_cvt_f32_i32_e32 v181, v123
	v_cvt_f32_i32_e32 v180, v122
	v_lshl_add_u64 v[172:173], v[118:119], 0, v[116:117]
	v_cvt_f32_i32_e32 v183, v125
	v_cvt_f32_i32_e32 v182, v124
	v_cvt_f32_i32_e32 v111, v111
	v_cvt_f32_i32_e32 v110, v110
	v_cvt_f32_i32_e32 v103, v103
	v_cvt_f32_i32_e32 v102, v102
	v_cvt_f32_i32_e32 v113, v113
	v_cvt_f32_i32_e32 v112, v112
	v_cvt_f32_i32_e32 v107, v107
	v_cvt_f32_i32_e32 v106, v106
	v_cvt_f32_i32_e32 v99, v99
	v_cvt_f32_i32_e32 v98, v98
	v_cvt_f32_i32_e32 v101, v101
	v_cvt_f32_i32_e32 v100, v100
	v_cvt_f32_i32_e32 v109, v109
	v_cvt_f32_i32_e32 v108, v108
	v_cvt_f32_i32_e32 v105, v105
	v_cvt_f32_i32_e32 v104, v104
	v_cvt_f32_i32_e32 v95, v95
	v_cvt_f32_i32_e32 v94, v94
	v_cvt_f32_i32_e32 v87, v87
	v_cvt_f32_i32_e32 v86, v86
	v_cvt_f32_i32_e32 v97, v97
	v_cvt_f32_i32_e32 v96, v96
	v_cvt_f32_i32_e32 v91, v91
	v_cvt_f32_i32_e32 v90, v90
	v_cvt_f32_i32_e32 v83, v83
	v_cvt_f32_i32_e32 v82, v82
	v_cvt_f32_i32_e32 v85, v85
	v_cvt_f32_i32_e32 v84, v84
	v_cvt_f32_i32_e32 v93, v93
	v_cvt_f32_i32_e32 v92, v92
	v_cvt_f32_i32_e32 v89, v89
	v_cvt_f32_i32_e32 v88, v88
	v_cvt_f32_i32_e32 v79, v79
	v_cvt_f32_i32_e32 v78, v78
	v_cvt_f32_i32_e32 v81, v81
	v_cvt_f32_i32_e32 v80, v80
	v_cvt_f32_i32_e32 v71, v71
	v_cvt_f32_i32_e32 v70, v70
	v_cvt_f32_i32_e32 v75, v75
	v_cvt_f32_i32_e32 v74, v74
	v_cvt_f32_i32_e32 v67, v67
	v_cvt_f32_i32_e32 v66, v66
	v_cvt_f32_i32_e32 v69, v69
	v_cvt_f32_i32_e32 v68, v68
	v_cvt_f32_i32_e32 v77, v77
	v_cvt_f32_i32_e32 v76, v76
	v_cvt_f32_i32_e32 v73, v73
	v_cvt_f32_i32_e32 v72, v72
	v_cvt_f32_i32_e32 v63, v63
	v_cvt_f32_i32_e32 v62, v62
	v_cvt_f32_i32_e32 v65, v65
	v_cvt_f32_i32_e32 v64, v64
	s_waitcnt vmcnt(0)
	s_and_b64 vcc, exec, s[6:7]
	s_cbranch_vccz .Lalign_p2
	s_barrier
.Lalign_p2:
	v_pk_mul_f32 v[120:121], v[148:149], s[40:41] op_sel_hi:[1,0]
	v_pk_mul_f32 v[128:129], v[164:165], s[40:41] op_sel_hi:[1,0]
	v_pk_mul_f32 v[118:119], v[150:151], s[40:41] op_sel_hi:[1,0]
	v_pk_mul_f32 v[122:123], v[162:163], s[40:41] op_sel_hi:[1,0]
	v_pk_mul_f32 v[126:127], v[166:167], s[40:41] op_sel_hi:[1,0]
	v_pk_mul_f32 v[148:149], v[170:171], s[40:41] op_sel_hi:[1,0]
	v_pk_mul_f32 v[162:163], v[120:121], v[176:177]
	v_pk_mul_f32 v[170:171], v[128:129], v[184:185]
	v_pk_mul_f32 v[124:125], v[160:161], s[40:41] op_sel_hi:[1,0]
	v_pk_mul_f32 v[150:151], v[168:169], s[40:41] op_sel_hi:[1,0]
	v_pk_mul_f32 v[160:161], v[118:119], v[178:179]
	v_pk_mul_f32 v[168:169], v[126:127], v[186:187]
	v_pk_mul_f32 v[162:163], v[162:163], v[174:175] op_sel_hi:[1,0]
	v_pk_mul_f32 v[170:171], v[170:171], v[174:175] op_sel_hi:[1,0]
	v_pk_mul_f32 v[160:161], v[160:161], v[174:175] op_sel_hi:[1,0]
	v_pk_mul_f32 v[168:169], v[168:169], v[174:175] op_sel_hi:[1,0]
	v_mul_f32_e32 v147, v162, v170
	v_mul_f32_e32 v159, 0xbfb8aa3b, v162
	v_mul_f32_e32 v162, v163, v171
	v_mul_f32_e32 v163, 0xbfb8aa3b, v163
	v_mul_f32_e32 v168, v160, v168
	v_mul_f32_e32 v160, 0xbfb8aa3b, v160
	v_exp_f32_e32 v159, v159
	v_exp_f32_e32 v163, v163
	v_exp_f32_e32 v160, v160
	v_pk_mul_f32 v[164:165], v[122:123], v[182:183]
	v_pk_mul_f32 v[166:167], v[124:125], v[180:181]
	v_pk_mul_f32 v[176:177], v[148:149], v[190:191]
	v_pk_mul_f32 v[178:179], v[150:151], v[188:189]
	v_add_f32_e32 v159, 1.0, v159
	v_add_f32_e32 v163, 1.0, v163
	v_pk_mul_f32 v[164:165], v[164:165], v[174:175] op_sel_hi:[1,0]
	v_pk_mul_f32 v[166:167], v[166:167], v[174:175] op_sel_hi:[1,0]
	v_pk_mul_f32 v[176:177], v[176:177], v[174:175] op_sel_hi:[1,0]
	v_pk_mul_f32 v[174:175], v[178:179], v[174:175] op_sel_hi:[1,0]
	v_add_f32_e32 v160, 1.0, v160
	v_rcp_f32_e32 v159, v159
	v_rcp_f32_e32 v163, v163
	v_mul_f32_e32 v169, v161, v169
	v_mul_f32_e32 v161, 0xbfb8aa3b, v161
	v_mul_f32_e32 v170, v166, v174
	v_mul_f32_e32 v166, 0xbfb8aa3b, v166
	v_mul_f32_e32 v171, v167, v175
	v_mul_f32_e32 v167, 0xbfb8aa3b, v167
	v_rcp_f32_e32 v160, v160
	v_exp_f32_e32 v161, v161
	v_exp_f32_e32 v166, v166
	v_exp_f32_e32 v167, v167
	v_mul_f32_e32 v174, 0xbfb8aa3b, v164
	v_mul_f32_e32 v175, 0xbfb8aa3b, v165
	v_exp_f32_e32 v174, v174
	v_mul_f32_e32 v147, v147, v159
	v_mul_f32_e32 v159, v162, v163
	v_mul_f32_e32 v162, v168, v160
	v_cvt_pkrtz_f16_f32 v160, v147, v159
	v_exp_f32_e32 v147, v175
	v_add_f32_e32 v161, 1.0, v161
	v_add_f32_e32 v166, 1.0, v166
	v_add_f32_e32 v167, 1.0, v167
	v_rcp_f32_e32 v161, v161
	v_rcp_f32_e32 v166, v166
	v_rcp_f32_e32 v167, v167
	v_add_f32_e32 v159, 1.0, v174
	v_rcp_f32_e32 v159, v159
	v_add_f32_e32 v147, 1.0, v147
	v_rcp_f32_e32 v147, v147
	v_mul_f32_e32 v161, v169, v161
	v_mul_f32_e32 v163, v170, v166
	v_mul_f32_e32 v166, v171, v167
	v_cvt_pkrtz_f16_f32 v161, v162, v161
	v_cvt_pkrtz_f16_f32 v162, v163, v166
	v_mul_f32_e32 v163, v164, v176
	v_mul_f32_e32 v159, v163, v159
	v_mul_f32_e32 v163, v165, v177
	v_mul_f32_e32 v147, v163, v147
	v_cvt_pkrtz_f16_f32 v163, v159, v147
	global_store_dwordx4 v[172:173], v[160:163], off
	v_pk_mul_f32 v[110:111], v[120:121], v[110:111]
	v_pk_mul_f32 v[102:103], v[128:129], v[102:103]
	v_or_b32_e32 v160, 16, v146
	v_ashrrev_i32_e32 v161, 31, v160
	v_lshl_add_u64 v[162:163], v[160:161], 2, s[70:71]
	v_mov_b32_e32 v162, v192
	v_pk_mul_f32 v[112:113], v[118:119], v[112:113]
	v_pk_mul_f32 v[106:107], v[124:125], v[106:107]
	v_pk_mul_f32 v[100:101], v[148:149], v[100:101]
	v_pk_mul_f32 v[98:99], v[150:151], v[98:99]
	v_pk_mul_f32 v[108:109], v[122:123], v[108:109]
	v_pk_mul_f32 v[104:105], v[126:127], v[104:105]
	v_mad_i64_i32 v[160:161], s[8:9], v160, s91, v[114:115]
	v_lshl_add_u64 v[160:161], v[160:161], 0, v[116:117]
	v_pk_mul_f32 v[94:95], v[120:121], v[94:95]
	v_pk_mul_f32 v[86:87], v[128:129], v[86:87]
	v_pk_mul_f32 v[96:97], v[118:119], v[96:97]
	v_pk_mul_f32 v[90:91], v[124:125], v[90:91]
	v_pk_mul_f32 v[84:85], v[148:149], v[84:85]
	v_pk_mul_f32 v[82:83], v[150:151], v[82:83]
	v_pk_mul_f32 v[92:93], v[122:123], v[92:93]
	v_pk_mul_f32 v[88:89], v[126:127], v[88:89]
	v_pk_mul_f32 v[80:81], v[118:119], v[80:81]
	v_pk_mul_f32 v[78:79], v[120:121], v[78:79]
	v_pk_mul_f32 v[70:71], v[128:129], v[70:71]
	v_pk_mul_f32 v[74:75], v[124:125], v[74:75]
	v_pk_mul_f32 v[68:69], v[148:149], v[68:69]
	v_pk_mul_f32 v[66:67], v[150:151], v[66:67]
	v_pk_mul_f32 v[76:77], v[122:123], v[76:77]
	v_pk_mul_f32 v[72:73], v[126:127], v[72:73]
	v_cvt_f32_i32_e32 v59, v59
	v_cvt_f32_i32_e32 v58, v58
	v_cvt_f32_i32_e32 v61, v61
	v_cvt_f32_i32_e32 v60, v60
	v_cvt_f32_i32_e32 v55, v55
	v_cvt_f32_i32_e32 v54, v54
	v_cvt_f32_i32_e32 v57, v57
	v_cvt_f32_i32_e32 v56, v56
	v_cvt_f32_i32_e32 v51, v51
	v_cvt_f32_i32_e32 v50, v50
	v_cvt_f32_i32_e32 v53, v53
	v_cvt_f32_i32_e32 v52, v52
	v_pk_mul_f32 v[64:65], v[118:119], v[64:65]
	v_pk_mul_f32 v[62:63], v[120:121], v[62:63]
	v_pk_mul_f32 v[60:61], v[122:123], v[60:61]
	v_pk_mul_f32 v[58:59], v[124:125], v[58:59]
	v_pk_mul_f32 v[56:57], v[126:127], v[56:57]
	v_pk_mul_f32 v[54:55], v[128:129], v[54:55]
	v_pk_mul_f32 v[52:53], v[148:149], v[52:53]
	v_pk_mul_f32 v[50:51], v[150:151], v[50:51]
	v_cvt_f32_i32_e32 v47, v47
	v_cvt_f32_i32_e32 v46, v46
	v_cvt_f32_i32_e32 v49, v49
	v_cvt_f32_i32_e32 v48, v48
	v_cvt_f32_i32_e32 v43, v43
	v_cvt_f32_i32_e32 v42, v42
	v_cvt_f32_i32_e32 v45, v45
	v_cvt_f32_i32_e32 v44, v44
	v_cvt_f32_i32_e32 v39, v39
	v_cvt_f32_i32_e32 v38, v38
	v_cvt_f32_i32_e32 v41, v41
	v_cvt_f32_i32_e32 v40, v40
	v_cvt_f32_i32_e32 v35, v35
	v_cvt_f32_i32_e32 v34, v34
	v_cvt_f32_i32_e32 v37, v37
	v_cvt_f32_i32_e32 v36, v36
	v_pk_mul_f32 v[48:49], v[118:119], v[48:49]
	v_pk_mul_f32 v[46:47], v[120:121], v[46:47]
	v_pk_mul_f32 v[44:45], v[122:123], v[44:45]
	v_pk_mul_f32 v[42:43], v[124:125], v[42:43]
	v_pk_mul_f32 v[40:41], v[126:127], v[40:41]
	v_pk_mul_f32 v[38:39], v[128:129], v[38:39]
	v_pk_mul_f32 v[36:37], v[148:149], v[36:37]
	v_pk_mul_f32 v[34:35], v[150:151], v[34:35]
	v_cvt_f32_i32_e32 v31, v31
	v_cvt_f32_i32_e32 v30, v30
	v_cvt_f32_i32_e32 v33, v33
	v_cvt_f32_i32_e32 v32, v32
	v_cvt_f32_i32_e32 v27, v27
	v_cvt_f32_i32_e32 v26, v26
	v_cvt_f32_i32_e32 v29, v29
	v_cvt_f32_i32_e32 v28, v28
	v_cvt_f32_i32_e32 v23, v23
	v_cvt_f32_i32_e32 v22, v22
	v_pk_mul_f32 v[110:111], v[110:111], v[162:163] op_sel_hi:[1,0]
	v_pk_mul_f32 v[102:103], v[102:103], v[162:163] op_sel_hi:[1,0]
	v_pk_mul_f32 v[112:113], v[112:113], v[162:163] op_sel_hi:[1,0]
	v_pk_mul_f32 v[106:107], v[106:107], v[162:163] op_sel_hi:[1,0]
	v_pk_mul_f32 v[164:165], v[100:101], v[162:163] op_sel_hi:[1,0]
	v_pk_mul_f32 v[98:99], v[98:99], v[162:163] op_sel_hi:[1,0]
	v_mul_f32_e32 v100, v110, v102
	v_mul_f32_e32 v101, 0xbfb8aa3b, v110
	v_mul_f32_e32 v102, v111, v103
	v_mul_f32_e32 v103, 0xbfb8aa3b, v111
	v_mul_f32_e32 v110, 0xbfb8aa3b, v112
	v_mul_f32_e32 v111, 0xbfb8aa3b, v113
	v_mul_f32_e32 v98, v106, v98
	v_mul_f32_e32 v106, 0xbfb8aa3b, v106
	v_exp_f32_e32 v101, v101
	v_exp_f32_e32 v103, v103
	v_mul_f32_e32 v99, v107, v99
	v_mul_f32_e32 v107, 0xbfb8aa3b, v107
	v_exp_f32_e32 v110, v110
	v_exp_f32_e32 v111, v111
	v_exp_f32_e32 v106, v106
	v_exp_f32_e32 v107, v107
	v_pk_mul_f32 v[108:109], v[108:109], v[162:163] op_sel_hi:[1,0]
	v_pk_mul_f32 v[104:105], v[104:105], v[162:163] op_sel_hi:[1,0]
	v_add_f32_e32 v101, 1.0, v101
	v_add_f32_e32 v103, 1.0, v103
	v_mul_f32_e32 v104, v112, v104
	v_mul_f32_e32 v112, 0xbfb8aa3b, v108
	v_add_f32_e32 v110, 1.0, v110
	v_add_f32_e32 v111, 1.0, v111
	v_add_f32_e32 v106, 1.0, v106
	v_rcp_f32_e32 v101, v101
	v_rcp_f32_e32 v103, v103
	v_mul_f32_e32 v105, v113, v105
	v_mul_f32_e32 v113, 0xbfb8aa3b, v109
	v_exp_f32_e32 v112, v112
	v_add_f32_e32 v107, 1.0, v107
	v_rcp_f32_e32 v110, v110
	v_rcp_f32_e32 v111, v111
	v_rcp_f32_e32 v106, v106
	v_exp_f32_e32 v113, v113
	v_rcp_f32_e32 v107, v107
	v_mul_f32_e32 v100, v100, v101
	v_mul_f32_e32 v101, v102, v103
	v_mul_f32_e32 v102, v104, v110
	v_mul_f32_e32 v103, v105, v111
	v_mul_f32_e32 v104, v98, v106
	v_cvt_pkrtz_f16_f32 v98, v100, v101
	v_add_f32_e32 v101, 1.0, v112
	v_mul_f32_e32 v105, v99, v107
	v_cvt_pkrtz_f16_f32 v99, v102, v103
	v_rcp_f32_e32 v101, v101
	v_add_f32_e32 v102, 1.0, v113
	v_rcp_f32_e32 v102, v102
	v_mul_f32_e32 v103, v108, v164
	v_mul_f32_e32 v101, v103, v101
	v_mul_f32_e32 v103, v109, v165
	v_mul_f32_e32 v102, v103, v102
	v_cvt_pkrtz_f16_f32 v100, v104, v105
	v_cvt_pkrtz_f16_f32 v101, v101, v102
	global_store_dwordx4 v[160:161], v[98:101], off
	v_cvt_f32_i32_e32 v25, v25
	v_cvt_f32_i32_e32 v24, v24
	v_or_b32_e32 v98, 32, v146
	v_ashrrev_i32_e32 v99, 31, v98
	v_lshl_add_u64 v[100:101], v[98:99], 2, s[70:71]
	v_mov_b32_e32 v100, v193
	v_mad_i64_i32 v[98:99], s[8:9], v98, s91, v[114:115]
	v_lshl_add_u64 v[98:99], v[98:99], 0, v[116:117]
	v_cvt_f32_i32_e32 v19, v19
	v_cvt_f32_i32_e32 v18, v18
	v_cvt_f32_i32_e32 v21, v21
	v_cvt_f32_i32_e32 v20, v20
	v_pk_mul_f32 v[32:33], v[118:119], v[32:33]
	v_pk_mul_f32 v[30:31], v[120:121], v[30:31]
	v_pk_mul_f32 v[28:29], v[122:123], v[28:29]
	v_pk_mul_f32 v[26:27], v[124:125], v[26:27]
	v_pk_mul_f32 v[24:25], v[126:127], v[24:25]
	v_pk_mul_f32 v[22:23], v[128:129], v[22:23]
	v_pk_mul_f32 v[20:21], v[148:149], v[20:21]
	v_pk_mul_f32 v[18:19], v[150:151], v[18:19]
	v_cvt_f32_i32_e32 v15, v15
	v_cvt_f32_i32_e32 v14, v14
	v_cvt_f32_i32_e32 v17, v17
	v_cvt_f32_i32_e32 v16, v16
	v_cvt_f32_i32_e32 v11, v11
	v_cvt_f32_i32_e32 v10, v10
	v_cvt_f32_i32_e32 v13, v13
	v_cvt_f32_i32_e32 v12, v12
	v_cvt_f32_i32_e32 v7, v7
	v_cvt_f32_i32_e32 v6, v6
	v_cvt_f32_i32_e32 v9, v9
	v_cvt_f32_i32_e32 v8, v8
	v_cvt_f32_i32_e32 v3, v3
	v_cvt_f32_i32_e32 v2, v2
	v_cvt_f32_i32_e32 v5, v5
	v_cvt_f32_i32_e32 v4, v4
	v_pk_mul_f32 v[16:17], v[118:119], v[16:17]
	v_pk_mul_f32 v[14:15], v[120:121], v[14:15]
	v_pk_mul_f32 v[12:13], v[122:123], v[12:13]
	v_pk_mul_f32 v[10:11], v[124:125], v[10:11]
	v_pk_mul_f32 v[8:9], v[126:127], v[8:9]
	v_pk_mul_f32 v[6:7], v[128:129], v[6:7]
	v_pk_mul_f32 v[4:5], v[148:149], v[4:5]
	v_pk_mul_f32 v[2:3], v[150:151], v[2:3]
	s_andn2_b64 vcc, exec, s[2:3]
	s_mov_b64 s[2:3], -1
	v_pk_mul_f32 v[94:95], v[94:95], v[100:101] op_sel_hi:[1,0]
	v_pk_mul_f32 v[86:87], v[86:87], v[100:101] op_sel_hi:[1,0]
	v_pk_mul_f32 v[96:97], v[96:97], v[100:101] op_sel_hi:[1,0]
	v_pk_mul_f32 v[90:91], v[90:91], v[100:101] op_sel_hi:[1,0]
	v_pk_mul_f32 v[102:103], v[84:85], v[100:101] op_sel_hi:[1,0]
	v_pk_mul_f32 v[82:83], v[82:83], v[100:101] op_sel_hi:[1,0]
	v_mul_f32_e32 v84, v94, v86
	v_mul_f32_e32 v85, 0xbfb8aa3b, v94
	v_mul_f32_e32 v86, v95, v87
	v_mul_f32_e32 v87, 0xbfb8aa3b, v95
	v_mul_f32_e32 v94, 0xbfb8aa3b, v96
	v_mul_f32_e32 v82, v90, v82
	v_mul_f32_e32 v90, 0xbfb8aa3b, v90
	v_exp_f32_e32 v85, v85
	v_exp_f32_e32 v87, v87
	v_exp_f32_e32 v94, v94
	v_exp_f32_e32 v90, v90
	v_mul_f32_e32 v95, 0xbfb8aa3b, v97
	v_pk_mul_f32 v[92:93], v[92:93], v[100:101] op_sel_hi:[1,0]
	v_pk_mul_f32 v[88:89], v[88:89], v[100:101] op_sel_hi:[1,0]
	v_mul_f32_e32 v83, v91, v83
	v_mul_f32_e32 v91, 0xbfb8aa3b, v91
	v_exp_f32_e32 v95, v95
	v_add_f32_e32 v85, 1.0, v85
	v_add_f32_e32 v87, 1.0, v87
	v_mul_f32_e32 v88, v96, v88
	v_mul_f32_e32 v89, v97, v89
	v_mul_f32_e32 v96, 0xbfb8aa3b, v92
	v_mul_f32_e32 v97, 0xbfb8aa3b, v93
	v_exp_f32_e32 v91, v91
	v_add_f32_e32 v94, 1.0, v94
	v_add_f32_e32 v90, 1.0, v90
	v_rcp_f32_e32 v85, v85
	v_rcp_f32_e32 v87, v87
	v_exp_f32_e32 v96, v96
	v_exp_f32_e32 v97, v97
	v_rcp_f32_e32 v94, v94
	v_rcp_f32_e32 v90, v90
	v_add_f32_e32 v95, 1.0, v95
	v_add_f32_e32 v91, 1.0, v91
	v_rcp_f32_e32 v95, v95
	v_mul_f32_e32 v84, v84, v85
	v_mul_f32_e32 v85, v86, v87
	v_add_f32_e32 v96, 1.0, v96
	v_rcp_f32_e32 v91, v91
	v_mul_f32_e32 v86, v88, v94
	v_mul_f32_e32 v88, v82, v90
	v_cvt_pkrtz_f16_f32 v82, v84, v85
	v_add_f32_e32 v85, 1.0, v97
	v_rcp_f32_e32 v96, v96
	v_rcp_f32_e32 v85, v85
	v_mul_f32_e32 v87, v89, v95
	v_mul_f32_e32 v89, v83, v91
	v_cvt_pkrtz_f16_f32 v83, v86, v87
	v_mul_f32_e32 v86, v92, v102
	v_mul_f32_e32 v87, v93, v103
	v_mul_f32_e32 v86, v86, v96
	v_mul_f32_e32 v85, v87, v85
	v_cvt_pkrtz_f16_f32 v84, v88, v89
	v_cvt_pkrtz_f16_f32 v85, v86, v85
	global_store_dwordx4 v[98:99], v[82:85], off
	s_nop 1
	v_or_b32_e32 v82, 48, v146
	v_ashrrev_i32_e32 v83, 31, v82
	v_lshl_add_u64 v[84:85], v[82:83], 2, s[70:71]
	v_mov_b32_e32 v84, v194
	v_mad_i64_i32 v[82:83], s[8:9], v82, s91, v[114:115]
	v_lshl_add_u64 v[82:83], v[82:83], 0, v[116:117]
	v_pk_mul_f32 v[80:81], v[80:81], v[84:85] op_sel_hi:[1,0]
	v_pk_mul_f32 v[78:79], v[78:79], v[84:85] op_sel_hi:[1,0]
	v_pk_mul_f32 v[70:71], v[70:71], v[84:85] op_sel_hi:[1,0]
	v_pk_mul_f32 v[74:75], v[74:75], v[84:85] op_sel_hi:[1,0]
	v_pk_mul_f32 v[86:87], v[68:69], v[84:85] op_sel_hi:[1,0]
	v_pk_mul_f32 v[66:67], v[66:67], v[84:85] op_sel_hi:[1,0]
	v_mul_f32_e32 v68, v78, v70
	v_mul_f32_e32 v69, 0xbfb8aa3b, v78
	v_mul_f32_e32 v70, v79, v71
	v_mul_f32_e32 v71, 0xbfb8aa3b, v79
	v_mul_f32_e32 v78, 0xbfb8aa3b, v80
	v_mul_f32_e32 v79, 0xbfb8aa3b, v81
	v_pk_mul_f32 v[76:77], v[76:77], v[84:85] op_sel_hi:[1,0]
	v_pk_mul_f32 v[72:73], v[72:73], v[84:85] op_sel_hi:[1,0]
	v_mul_f32_e32 v66, v74, v66
	v_mul_f32_e32 v74, 0xbfb8aa3b, v74
	v_mul_f32_e32 v67, v75, v67
	v_mul_f32_e32 v75, 0xbfb8aa3b, v75
	v_exp_f32_e32 v69, v69
	v_exp_f32_e32 v71, v71
	v_exp_f32_e32 v78, v78
	v_exp_f32_e32 v79, v79
	v_mul_f32_e32 v72, v80, v72
	v_mul_f32_e32 v73, v81, v73
	v_mul_f32_e32 v80, 0xbfb8aa3b, v76
	v_mul_f32_e32 v81, 0xbfb8aa3b, v77
	v_exp_f32_e32 v74, v74
	v_exp_f32_e32 v75, v75
	v_exp_f32_e32 v80, v80
	v_exp_f32_e32 v81, v81
	v_add_f32_e32 v69, 1.0, v69
	v_add_f32_e32 v71, 1.0, v71
	v_add_f32_e32 v78, 1.0, v78
	v_add_f32_e32 v79, 1.0, v79
	v_add_f32_e32 v74, 1.0, v74
	v_add_f32_e32 v75, 1.0, v75
	v_rcp_f32_e32 v69, v69
	v_rcp_f32_e32 v71, v71
	v_rcp_f32_e32 v78, v78
	v_rcp_f32_e32 v79, v79
	v_add_f32_e32 v80, 1.0, v80
	v_add_f32_e32 v81, 1.0, v81
	v_rcp_f32_e32 v74, v74
	v_rcp_f32_e32 v75, v75
	v_rcp_f32_e32 v80, v80
	v_rcp_f32_e32 v81, v81
	v_mul_f32_e32 v68, v68, v69
	v_mul_f32_e32 v69, v70, v71
	v_mul_f32_e32 v70, v72, v78
	v_mul_f32_e32 v71, v73, v79
	v_mul_f32_e32 v72, v66, v74
	v_mul_f32_e32 v73, v67, v75
	v_cvt_pkrtz_f16_f32 v66, v68, v69
	v_cvt_pkrtz_f16_f32 v67, v70, v71
	v_mul_f32_e32 v69, v76, v86
	v_mul_f32_e32 v70, v77, v87
	v_mul_f32_e32 v69, v69, v80
	v_mul_f32_e32 v70, v70, v81
	v_cvt_pkrtz_f16_f32 v68, v72, v73
	v_cvt_pkrtz_f16_f32 v69, v69, v70
	global_store_dwordx4 v[82:83], v[66:69], off
	s_nop 1
	v_mov_b32_e32 v66, v195
	v_add_u32_e32 v67, 0x80, v146
	v_mad_i64_i32 v[68:69], s[8:9], v67, s91, v[114:115]
	v_lshl_add_u64 v[68:69], v[68:69], 0, v[116:117]
	v_pk_mul_f32 v[64:65], v[64:65], v[66:67] op_sel_hi:[1,0]
	v_pk_mul_f32 v[62:63], v[62:63], v[66:67] op_sel_hi:[1,0]
	v_pk_mul_f32 v[60:61], v[60:61], v[66:67] op_sel_hi:[1,0]
	v_pk_mul_f32 v[58:59], v[58:59], v[66:67] op_sel_hi:[1,0]
	v_pk_mul_f32 v[56:57], v[56:57], v[66:67] op_sel_hi:[1,0]
	v_pk_mul_f32 v[54:55], v[54:55], v[66:67] op_sel_hi:[1,0]
	v_pk_mul_f32 v[52:53], v[52:53], v[66:67] op_sel_hi:[1,0]
	v_pk_mul_f32 v[50:51], v[50:51], v[66:67] op_sel_hi:[1,0]
	v_mul_f32_e32 v54, v62, v54
	v_mul_f32_e32 v62, 0xbfb8aa3b, v62
	v_mul_f32_e32 v55, v63, v55
	v_mul_f32_e32 v63, 0xbfb8aa3b, v63
	v_mul_f32_e32 v56, v64, v56
	v_mul_f32_e32 v64, 0xbfb8aa3b, v64
	v_mul_f32_e32 v57, v65, v57
	v_mul_f32_e32 v65, 0xbfb8aa3b, v65
	v_mul_f32_e32 v50, v58, v50
	v_mul_f32_e32 v58, 0xbfb8aa3b, v58
	v_mul_f32_e32 v51, v59, v51
	v_mul_f32_e32 v59, 0xbfb8aa3b, v59
	v_mul_f32_e32 v52, v60, v52
	v_mul_f32_e32 v60, 0xbfb8aa3b, v60
	v_mul_f32_e32 v53, v61, v53
	v_mul_f32_e32 v61, 0xbfb8aa3b, v61
	v_exp_f32_e32 v62, v62
	v_exp_f32_e32 v63, v63
	v_exp_f32_e32 v64, v64
	v_exp_f32_e32 v65, v65
	v_exp_f32_e32 v58, v58
	v_exp_f32_e32 v59, v59
	v_exp_f32_e32 v60, v60
	v_exp_f32_e32 v61, v61
	v_add_f32_e32 v62, 1.0, v62
	v_add_f32_e32 v63, 1.0, v63
	v_add_f32_e32 v64, 1.0, v64
	v_add_f32_e32 v65, 1.0, v65
	v_add_f32_e32 v58, 1.0, v58
	v_add_f32_e32 v59, 1.0, v59
	v_add_f32_e32 v60, 1.0, v60
	v_add_f32_e32 v61, 1.0, v61
	v_rcp_f32_e32 v62, v62
	v_rcp_f32_e32 v63, v63
	v_rcp_f32_e32 v64, v64
	v_rcp_f32_e32 v65, v65
	v_rcp_f32_e32 v58, v58
	v_rcp_f32_e32 v59, v59
	v_rcp_f32_e32 v60, v60
	v_rcp_f32_e32 v61, v61
	v_mul_f32_e32 v54, v54, v62
	v_mul_f32_e32 v55, v55, v63
	v_mul_f32_e32 v56, v56, v64
	v_mul_f32_e32 v57, v57, v65
	v_mul_f32_e32 v58, v50, v58
	v_mul_f32_e32 v59, v51, v59
	v_mul_f32_e32 v60, v52, v60
	v_mul_f32_e32 v53, v53, v61
	v_cvt_pkrtz_f16_f32 v50, v54, v55
	v_cvt_pkrtz_f16_f32 v51, v56, v57
	v_cvt_pkrtz_f16_f32 v52, v58, v59
	v_cvt_pkrtz_f16_f32 v53, v60, v53
	global_store_dwordx4 v[68:69], v[50:53], off
	s_nop 1
	v_mov_b32_e32 v50, v196
	v_add_u32_e32 v51, 0x90, v146
	v_mad_i64_i32 v[52:53], s[8:9], v51, s91, v[114:115]
	v_lshl_add_u64 v[52:53], v[52:53], 0, v[116:117]
	v_pk_mul_f32 v[48:49], v[48:49], v[50:51] op_sel_hi:[1,0]
	v_pk_mul_f32 v[46:47], v[46:47], v[50:51] op_sel_hi:[1,0]
	v_pk_mul_f32 v[44:45], v[44:45], v[50:51] op_sel_hi:[1,0]
	v_pk_mul_f32 v[42:43], v[42:43], v[50:51] op_sel_hi:[1,0]
	v_pk_mul_f32 v[40:41], v[40:41], v[50:51] op_sel_hi:[1,0]
	v_pk_mul_f32 v[38:39], v[38:39], v[50:51] op_sel_hi:[1,0]
	v_pk_mul_f32 v[36:37], v[36:37], v[50:51] op_sel_hi:[1,0]
	v_pk_mul_f32 v[34:35], v[34:35], v[50:51] op_sel_hi:[1,0]
	v_mul_f32_e32 v38, v46, v38
	v_mul_f32_e32 v46, 0xbfb8aa3b, v46
	v_mul_f32_e32 v39, v47, v39
	v_mul_f32_e32 v47, 0xbfb8aa3b, v47
	v_mul_f32_e32 v40, v48, v40
	v_mul_f32_e32 v48, 0xbfb8aa3b, v48
	v_mul_f32_e32 v41, v49, v41
	v_mul_f32_e32 v49, 0xbfb8aa3b, v49
	v_mul_f32_e32 v34, v42, v34
	v_mul_f32_e32 v42, 0xbfb8aa3b, v42
	v_mul_f32_e32 v35, v43, v35
	v_mul_f32_e32 v43, 0xbfb8aa3b, v43
	v_mul_f32_e32 v36, v44, v36
	v_mul_f32_e32 v44, 0xbfb8aa3b, v44
	v_mul_f32_e32 v37, v45, v37
	v_mul_f32_e32 v45, 0xbfb8aa3b, v45
	v_exp_f32_e32 v46, v46
	v_exp_f32_e32 v47, v47
	v_exp_f32_e32 v48, v48
	v_exp_f32_e32 v49, v49
	v_exp_f32_e32 v42, v42
	v_exp_f32_e32 v43, v43
	v_exp_f32_e32 v44, v44
	v_exp_f32_e32 v45, v45
	v_add_f32_e32 v46, 1.0, v46
	v_add_f32_e32 v47, 1.0, v47
	v_add_f32_e32 v48, 1.0, v48
	v_add_f32_e32 v49, 1.0, v49
	v_add_f32_e32 v42, 1.0, v42
	v_add_f32_e32 v43, 1.0, v43
	v_add_f32_e32 v44, 1.0, v44
	v_add_f32_e32 v45, 1.0, v45
	v_rcp_f32_e32 v46, v46
	v_rcp_f32_e32 v47, v47
	v_rcp_f32_e32 v48, v48
	v_rcp_f32_e32 v49, v49
	v_rcp_f32_e32 v42, v42
	v_rcp_f32_e32 v43, v43
	v_rcp_f32_e32 v44, v44
	v_rcp_f32_e32 v45, v45
	v_mul_f32_e32 v38, v38, v46
	v_mul_f32_e32 v39, v39, v47
	v_mul_f32_e32 v40, v40, v48
	v_mul_f32_e32 v41, v41, v49
	v_mul_f32_e32 v42, v34, v42
	v_mul_f32_e32 v43, v35, v43
	v_mul_f32_e32 v44, v36, v44
	v_mul_f32_e32 v37, v37, v45
	v_cvt_pkrtz_f16_f32 v34, v38, v39
	v_cvt_pkrtz_f16_f32 v35, v40, v41
	v_cvt_pkrtz_f16_f32 v36, v42, v43
	v_cvt_pkrtz_f16_f32 v37, v44, v37
	global_store_dwordx4 v[52:53], v[34:37], off
	s_nop 1
	v_mov_b32_e32 v34, v197
	v_add_u32_e32 v35, 0xa0, v146
	v_mad_i64_i32 v[36:37], s[8:9], v35, s91, v[114:115]
	v_lshl_add_u64 v[36:37], v[36:37], 0, v[116:117]
	v_pk_mul_f32 v[32:33], v[32:33], v[34:35] op_sel_hi:[1,0]
	v_pk_mul_f32 v[30:31], v[30:31], v[34:35] op_sel_hi:[1,0]
	v_pk_mul_f32 v[28:29], v[28:29], v[34:35] op_sel_hi:[1,0]
	v_pk_mul_f32 v[26:27], v[26:27], v[34:35] op_sel_hi:[1,0]
	v_pk_mul_f32 v[24:25], v[24:25], v[34:35] op_sel_hi:[1,0]
	v_pk_mul_f32 v[22:23], v[22:23], v[34:35] op_sel_hi:[1,0]
	v_pk_mul_f32 v[20:21], v[20:21], v[34:35] op_sel_hi:[1,0]
	v_pk_mul_f32 v[18:19], v[18:19], v[34:35] op_sel_hi:[1,0]
	v_mul_f32_e32 v22, v30, v22
	v_mul_f32_e32 v30, 0xbfb8aa3b, v30
	v_mul_f32_e32 v23, v31, v23
	v_mul_f32_e32 v31, 0xbfb8aa3b, v31
	v_mul_f32_e32 v24, v32, v24
	v_mul_f32_e32 v32, 0xbfb8aa3b, v32
	v_mul_f32_e32 v25, v33, v25
	v_mul_f32_e32 v33, 0xbfb8aa3b, v33
	v_mul_f32_e32 v18, v26, v18
	v_mul_f32_e32 v26, 0xbfb8aa3b, v26
	v_mul_f32_e32 v19, v27, v19
	v_mul_f32_e32 v27, 0xbfb8aa3b, v27
	v_mul_f32_e32 v20, v28, v20
	v_mul_f32_e32 v28, 0xbfb8aa3b, v28
	v_mul_f32_e32 v21, v29, v21
	v_mul_f32_e32 v29, 0xbfb8aa3b, v29
	v_exp_f32_e32 v30, v30
	v_exp_f32_e32 v31, v31
	v_exp_f32_e32 v32, v32
	v_exp_f32_e32 v33, v33
	v_exp_f32_e32 v26, v26
	v_exp_f32_e32 v27, v27
	v_exp_f32_e32 v28, v28
	v_exp_f32_e32 v29, v29
	v_add_f32_e32 v30, 1.0, v30
	v_add_f32_e32 v31, 1.0, v31
	v_add_f32_e32 v32, 1.0, v32
	v_add_f32_e32 v33, 1.0, v33
	v_add_f32_e32 v26, 1.0, v26
	v_add_f32_e32 v27, 1.0, v27
	v_add_f32_e32 v28, 1.0, v28
	v_add_f32_e32 v29, 1.0, v29
	v_rcp_f32_e32 v30, v30
	v_rcp_f32_e32 v31, v31
	v_rcp_f32_e32 v32, v32
	v_rcp_f32_e32 v33, v33
	v_rcp_f32_e32 v26, v26
	v_rcp_f32_e32 v27, v27
	v_rcp_f32_e32 v28, v28
	v_rcp_f32_e32 v29, v29
	v_mul_f32_e32 v22, v22, v30
	v_mul_f32_e32 v23, v23, v31
	v_mul_f32_e32 v24, v24, v32
	v_mul_f32_e32 v25, v25, v33
	v_mul_f32_e32 v26, v18, v26
	v_mul_f32_e32 v27, v19, v27
	v_mul_f32_e32 v28, v20, v28
	v_mul_f32_e32 v21, v21, v29
	v_cvt_pkrtz_f16_f32 v18, v22, v23
	v_cvt_pkrtz_f16_f32 v19, v24, v25
	v_cvt_pkrtz_f16_f32 v20, v26, v27
	v_cvt_pkrtz_f16_f32 v21, v28, v21
	global_store_dwordx4 v[36:37], v[18:21], off
	s_nop 1
	v_mov_b32_e32 v18, v198
	v_add_u32_e32 v19, 0xb0, v146
	v_mad_i64_i32 v[20:21], s[8:9], v19, s91, v[114:115]
	v_lshl_add_u64 v[20:21], v[20:21], 0, v[116:117]
	v_pk_mul_f32 v[16:17], v[16:17], v[18:19] op_sel_hi:[1,0]
	v_pk_mul_f32 v[14:15], v[14:15], v[18:19] op_sel_hi:[1,0]
	v_pk_mul_f32 v[12:13], v[12:13], v[18:19] op_sel_hi:[1,0]
	v_pk_mul_f32 v[10:11], v[10:11], v[18:19] op_sel_hi:[1,0]
	v_pk_mul_f32 v[8:9], v[8:9], v[18:19] op_sel_hi:[1,0]
	v_pk_mul_f32 v[6:7], v[6:7], v[18:19] op_sel_hi:[1,0]
	v_pk_mul_f32 v[4:5], v[4:5], v[18:19] op_sel_hi:[1,0]
	v_pk_mul_f32 v[2:3], v[2:3], v[18:19] op_sel_hi:[1,0]
	v_mul_f32_e32 v6, v14, v6
	v_mul_f32_e32 v14, 0xbfb8aa3b, v14
	v_mul_f32_e32 v7, v15, v7
	v_mul_f32_e32 v15, 0xbfb8aa3b, v15
	v_mul_f32_e32 v8, v16, v8
	v_mul_f32_e32 v16, 0xbfb8aa3b, v16
	v_mul_f32_e32 v9, v17, v9
	v_mul_f32_e32 v17, 0xbfb8aa3b, v17
	v_mul_f32_e32 v2, v10, v2
	v_mul_f32_e32 v10, 0xbfb8aa3b, v10
	v_mul_f32_e32 v3, v11, v3
	v_mul_f32_e32 v11, 0xbfb8aa3b, v11
	v_mul_f32_e32 v4, v12, v4
	v_mul_f32_e32 v12, 0xbfb8aa3b, v12
	v_mul_f32_e32 v5, v13, v5
	v_mul_f32_e32 v13, 0xbfb8aa3b, v13
	v_exp_f32_e32 v14, v14
	v_exp_f32_e32 v15, v15
	v_exp_f32_e32 v16, v16
	v_exp_f32_e32 v17, v17
	v_exp_f32_e32 v10, v10
	v_exp_f32_e32 v11, v11
	v_exp_f32_e32 v12, v12
	v_exp_f32_e32 v13, v13
	v_add_f32_e32 v14, 1.0, v14
	v_add_f32_e32 v15, 1.0, v15
	v_add_f32_e32 v16, 1.0, v16
	v_add_f32_e32 v17, 1.0, v17
	v_add_f32_e32 v10, 1.0, v10
	v_add_f32_e32 v11, 1.0, v11
	v_add_f32_e32 v12, 1.0, v12
	v_add_f32_e32 v13, 1.0, v13
	v_rcp_f32_e32 v14, v14
	v_rcp_f32_e32 v15, v15
	v_rcp_f32_e32 v16, v16
	v_rcp_f32_e32 v17, v17
	v_rcp_f32_e32 v10, v10
	v_rcp_f32_e32 v11, v11
	v_rcp_f32_e32 v12, v12
	v_rcp_f32_e32 v13, v13
	v_mul_f32_e32 v6, v6, v14
	v_mul_f32_e32 v7, v7, v15
	v_mul_f32_e32 v8, v8, v16
	v_mul_f32_e32 v9, v9, v17
	v_mul_f32_e32 v10, v2, v10
	v_mul_f32_e32 v11, v3, v11
	v_mul_f32_e32 v12, v4, v12
	v_mul_f32_e32 v5, v5, v13
	v_cvt_pkrtz_f16_f32 v2, v6, v7
	v_cvt_pkrtz_f16_f32 v3, v8, v9
	v_cvt_pkrtz_f16_f32 v4, v10, v11
	v_cvt_pkrtz_f16_f32 v5, v12, v5
	global_store_dwordx4 v[20:21], v[2:5], off
	s_cbranch_vccnz .LBB0_209
	s_andn2_b64 vcc, exec, s[0:1]
	s_cbranch_vccnz .LBB0_208
	s_barrier
	s_branch .LBB0_208

.LBB0_362:
	ds_read_b128 v[106:109], v168
	ds_read_b128 v[110:113], v168 offset:1024
	ds_read_b128 v[114:117], v168 offset:2048
	ds_read_b128 v[122:125], v168 offset:3072
	ds_read_b128 v[160:163], v169
	ds_read_b128 v[172:175], v169 offset:1024
	ds_read_b128 v[176:179], v169 offset:2048
	ds_read_b128 v[180:183], v169 offset:3072
	s_add_u32 s16, s6, 0xffea8080
	s_addc_u32 s17, s7, -1
	s_cmpk_eq_i32 s13, 0x52
	s_cselect_b32 s85, s51, s17
	s_cselect_b32 s84, s50, s16
	s_cselect_b32 s83, s81, s12
	s_cselect_b32 s82, s80, s8
	v_lshl_add_u64 v[216:217], s[6:7], 0, v[154:155]
	s_add_i32 m0, s56, 0xc000
	ds_read_b128 v[184:187], v170
	ds_read_b128 v[188:191], v170 offset:1024
	ds_read_b128 v[192:195], v170 offset:2048
	ds_read_b128 v[196:199], v170 offset:3072
	ds_read_b128 v[200:203], v170 offset:4096
	ds_read_b128 v[204:207], v170 offset:5120
	ds_read_b128 v[208:211], v170 offset:6144
	ds_read_b128 v[212:215], v170 offset:7168
	global_load_lds_dwordx4 v[216:217], off
	v_lshl_add_u64 v[216:217], s[6:7], 0, v[156:157]
	s_add_i32 m0, s56, 0xe000
	s_nop 0
	global_load_lds_dwordx4 v[216:217], off
	s_waitcnt vmcnt(8)
	s_waitcnt lgkmcnt(0)
	s_barrier
	s_setprio 1
	s_waitcnt lgkmcnt(0)
	v_mfma_i32_16x16x64_i8 v[142:145], v[106:109], v[184:187], v[142:145]
	v_mfma_i32_16x16x64_i8 v[138:141], v[114:117], v[184:187], v[138:141]
	v_mfma_i32_16x16x64_i8 v[126:129], v[106:109], v[192:195], v[126:129]
	v_mfma_i32_16x16x64_i8 v[118:121], v[114:117], v[192:195], v[118:121]
	v_mfma_i32_16x16x64_i8 v[94:97], v[106:109], v[200:203], v[94:97]
	v_mfma_i32_16x16x64_i8 v[90:93], v[114:117], v[200:203], v[90:93]
	v_mfma_i32_16x16x64_i8 v[78:81], v[106:109], v[208:211], v[78:81]
	v_mfma_i32_16x16x64_i8 v[74:77], v[114:117], v[208:211], v[74:77]
	v_mfma_i32_16x16x64_i8 v[142:145], v[110:113], v[188:191], v[142:145]
	v_mfma_i32_16x16x64_i8 v[138:141], v[122:125], v[188:191], v[138:141]
	v_mfma_i32_16x16x64_i8 v[126:129], v[110:113], v[196:199], v[126:129]
	v_mfma_i32_16x16x64_i8 v[118:121], v[122:125], v[196:199], v[118:121]
	v_mfma_i32_16x16x64_i8 v[94:97], v[110:113], v[204:207], v[94:97]
	v_mfma_i32_16x16x64_i8 v[90:93], v[122:125], v[204:207], v[90:93]
	v_mfma_i32_16x16x64_i8 v[78:81], v[110:113], v[212:215], v[78:81]
	v_mfma_i32_16x16x64_i8 v[74:77], v[122:125], v[212:215], v[74:77]
	s_setprio 0
	s_setprio 1
	v_mfma_i32_16x16x64_i8 v[134:137], v[160:163], v[184:187], v[134:137]
	v_mfma_i32_16x16x64_i8 v[130:133], v[176:179], v[184:187], v[130:133]
	v_mfma_i32_16x16x64_i8 v[102:105], v[160:163], v[192:195], v[102:105]
	v_mfma_i32_16x16x64_i8 v[98:101], v[176:179], v[192:195], v[98:101]
	v_mfma_i32_16x16x64_i8 v[86:89], v[160:163], v[200:203], v[86:89]
	v_mfma_i32_16x16x64_i8 v[82:85], v[176:179], v[200:203], v[82:85]
	v_mfma_i32_16x16x64_i8 v[70:73], v[160:163], v[208:211], v[70:73]
	v_mfma_i32_16x16x64_i8 v[66:69], v[176:179], v[208:211], v[66:69]
	v_mfma_i32_16x16x64_i8 v[134:137], v[172:175], v[188:191], v[134:137]
	v_mfma_i32_16x16x64_i8 v[130:133], v[180:183], v[188:191], v[130:133]
	v_mfma_i32_16x16x64_i8 v[102:105], v[172:175], v[196:199], v[102:105]
	v_mfma_i32_16x16x64_i8 v[98:101], v[180:183], v[196:199], v[98:101]
	v_mfma_i32_16x16x64_i8 v[86:89], v[172:175], v[204:207], v[86:89]
	v_mfma_i32_16x16x64_i8 v[82:85], v[180:183], v[204:207], v[82:85]
	v_mfma_i32_16x16x64_i8 v[70:73], v[172:175], v[212:215], v[70:73]
	v_mfma_i32_16x16x64_i8 v[66:69], v[180:183], v[212:215], v[66:69]
	s_setprio 0
	s_barrier
	s_add_i32 s16, s87, s35
	v_lshl_add_u64 v[216:217], s[82:83], 0, v[148:149]
	s_mov_b32 m0, s16
	ds_read_b128 v[184:187], v170 offset:16384
	ds_read_b128 v[188:191], v170 offset:17408
	ds_read_b128 v[192:195], v170 offset:18432
	ds_read_b128 v[196:199], v170 offset:19456
	ds_read_b128 v[200:203], v170 offset:20480
	ds_read_b128 v[204:207], v170 offset:21504
	ds_read_b128 v[208:211], v170 offset:22528
	ds_read_b128 v[212:215], v170 offset:23552
	global_load_lds_dwordx4 v[216:217], off
	s_add_i32 m0, s16, 0x2000
	s_add_u32 s16, s82, 0x158000
	v_lshl_add_u64 v[218:219], s[82:83], 0, v[152:153]
	s_addc_u32 s17, s83, 0
	s_add_i32 s18, s88, s35
	global_load_lds_dwordx4 v[218:219], off
	v_lshl_add_u64 v[220:221], s[16:17], 0, v[148:149]
	s_mov_b32 m0, s18
	v_lshl_add_u64 v[222:223], s[84:85], 0, v[150:151]
	global_load_lds_dwordx4 v[220:221], off
	v_lshl_add_u64 v[220:221], s[16:17], 0, v[152:153]
	s_add_i32 m0, s18, 0x2000
	s_nop 0
	global_load_lds_dwordx4 v[220:221], off
	v_lshl_add_u64 v[220:221], s[84:85], 0, v[146:147]
	s_mov_b32 m0, s56
	s_nop 0
	global_load_lds_dwordx4 v[220:221], off
	s_mov_b32 m0, s57
	s_nop 0
	global_load_lds_dwordx4 v[222:223], off
	s_waitcnt vmcnt(8)
	s_waitcnt lgkmcnt(0)
	s_barrier
	s_setprio 1
	s_waitcnt lgkmcnt(0)
	v_mfma_i32_16x16x64_i8 v[62:65], v[106:109], v[184:187], v[62:65]
	v_mfma_i32_16x16x64_i8 v[58:61], v[114:117], v[184:187], v[58:61]
	v_mfma_i32_16x16x64_i8 v[46:49], v[106:109], v[192:195], v[46:49]
	v_mfma_i32_16x16x64_i8 v[42:45], v[114:117], v[192:195], v[42:45]
	v_mfma_i32_16x16x64_i8 v[30:33], v[106:109], v[200:203], v[30:33]
	v_mfma_i32_16x16x64_i8 v[26:29], v[114:117], v[200:203], v[26:29]
	v_mfma_i32_16x16x64_i8 v[14:17], v[106:109], v[208:211], v[14:17]
	v_mfma_i32_16x16x64_i8 v[10:13], v[114:117], v[208:211], v[10:13]
	v_mfma_i32_16x16x64_i8 v[62:65], v[110:113], v[188:191], v[62:65]
	v_mfma_i32_16x16x64_i8 v[58:61], v[122:125], v[188:191], v[58:61]
	v_mfma_i32_16x16x64_i8 v[46:49], v[110:113], v[196:199], v[46:49]
	v_mfma_i32_16x16x64_i8 v[42:45], v[122:125], v[196:199], v[42:45]
	v_mfma_i32_16x16x64_i8 v[30:33], v[110:113], v[204:207], v[30:33]
	v_mfma_i32_16x16x64_i8 v[26:29], v[122:125], v[204:207], v[26:29]
	v_mfma_i32_16x16x64_i8 v[14:17], v[110:113], v[212:215], v[14:17]
	v_mfma_i32_16x16x64_i8 v[10:13], v[122:125], v[212:215], v[10:13]
	s_setprio 0
	s_setprio 1
	v_mfma_i32_16x16x64_i8 v[54:57], v[160:163], v[184:187], v[54:57]
	v_mfma_i32_16x16x64_i8 v[50:53], v[176:179], v[184:187], v[50:53]
	v_mfma_i32_16x16x64_i8 v[38:41], v[160:163], v[192:195], v[38:41]
	v_mfma_i32_16x16x64_i8 v[34:37], v[176:179], v[192:195], v[34:37]
	v_mfma_i32_16x16x64_i8 v[22:25], v[160:163], v[200:203], v[22:25]
	v_mfma_i32_16x16x64_i8 v[18:21], v[176:179], v[200:203], v[18:21]
	v_mfma_i32_16x16x64_i8 v[6:9], v[160:163], v[208:211], v[6:9]
	v_mfma_i32_16x16x64_i8 v[2:5], v[176:179], v[208:211], v[2:5]
	v_mfma_i32_16x16x64_i8 v[54:57], v[172:175], v[188:191], v[54:57]
	v_mfma_i32_16x16x64_i8 v[50:53], v[180:183], v[188:191], v[50:53]
	v_mfma_i32_16x16x64_i8 v[38:41], v[172:175], v[196:199], v[38:41]
	v_mfma_i32_16x16x64_i8 v[34:37], v[180:183], v[196:199], v[34:37]
	v_mfma_i32_16x16x64_i8 v[22:25], v[172:175], v[204:207], v[22:25]
	v_mfma_i32_16x16x64_i8 v[18:21], v[180:183], v[204:207], v[18:21]
	v_mfma_i32_16x16x64_i8 v[6:9], v[172:175], v[212:215], v[6:9]
	v_mfma_i32_16x16x64_i8 v[2:5], v[180:183], v[212:215], v[2:5]
	s_setprio 0
	s_barrier
	s_add_i32 s18, 0, 0x18000
	s_add_i32 s19, 0, 0x1c000
	v_add_u32_e32 v122, s18, v165
	v_add_u32_e32 v164, s19, v165
	ds_read_b128 v[106:109], v122
	ds_read_b128 v[110:113], v122 offset:1024
	ds_read_b128 v[114:117], v122 offset:2048
	ds_read_b128 v[122:125], v122 offset:3072
	ds_read_b128 v[160:163], v164
	ds_read_b128 v[172:175], v164 offset:1024
	ds_read_b128 v[176:179], v164 offset:2048
	ds_read_b128 v[180:183], v164 offset:3072
	s_add_u32 s16, s84, 0x158000
	s_addc_u32 s17, s85, 0
	s_mov_b32 m0, s58
	v_lshl_add_u64 v[224:225], s[16:17], 0, v[146:147]
	ds_read_b128 v[184:187], v170 offset:32768
	ds_read_b128 v[188:191], v170 offset:33792
	ds_read_b128 v[192:195], v170 offset:34816
	ds_read_b128 v[196:199], v170 offset:35840
	ds_read_b128 v[200:203], v170 offset:36864
	ds_read_b128 v[204:207], v170 offset:37888
	ds_read_b128 v[208:211], v170 offset:38912
	ds_read_b128 v[212:215], v170 offset:39936
	global_load_lds_dwordx4 v[224:225], off
	v_lshl_add_u64 v[224:225], s[16:17], 0, v[150:151]
	s_mov_b32 m0, s59
	s_nop 0
	global_load_lds_dwordx4 v[224:225], off
	s_waitcnt vmcnt(8)
	s_waitcnt lgkmcnt(0)
	s_barrier
	s_setprio 1
	s_waitcnt lgkmcnt(0)
	v_mfma_i32_16x16x64_i8 v[142:145], v[106:109], v[184:187], v[142:145]
	v_mfma_i32_16x16x64_i8 v[138:141], v[114:117], v[184:187], v[138:141]
	v_mfma_i32_16x16x64_i8 v[126:129], v[106:109], v[192:195], v[126:129]
	v_mfma_i32_16x16x64_i8 v[118:121], v[114:117], v[192:195], v[118:121]
	v_mfma_i32_16x16x64_i8 v[94:97], v[106:109], v[200:203], v[94:97]
	v_mfma_i32_16x16x64_i8 v[90:93], v[114:117], v[200:203], v[90:93]
	v_mfma_i32_16x16x64_i8 v[78:81], v[106:109], v[208:211], v[78:81]
	v_mfma_i32_16x16x64_i8 v[74:77], v[114:117], v[208:211], v[74:77]
	v_mfma_i32_16x16x64_i8 v[142:145], v[110:113], v[188:191], v[142:145]
	v_mfma_i32_16x16x64_i8 v[138:141], v[122:125], v[188:191], v[138:141]
	v_mfma_i32_16x16x64_i8 v[126:129], v[110:113], v[196:199], v[126:129]
	v_mfma_i32_16x16x64_i8 v[118:121], v[122:125], v[196:199], v[118:121]
	v_mfma_i32_16x16x64_i8 v[94:97], v[110:113], v[204:207], v[94:97]
	v_mfma_i32_16x16x64_i8 v[90:93], v[122:125], v[204:207], v[90:93]
	v_mfma_i32_16x16x64_i8 v[78:81], v[110:113], v[212:215], v[78:81]
	v_mfma_i32_16x16x64_i8 v[74:77], v[122:125], v[212:215], v[74:77]
	s_setprio 0
	s_setprio 1
	v_mfma_i32_16x16x64_i8 v[134:137], v[160:163], v[184:187], v[134:137]
	v_mfma_i32_16x16x64_i8 v[130:133], v[176:179], v[184:187], v[130:133]
	v_mfma_i32_16x16x64_i8 v[102:105], v[160:163], v[192:195], v[102:105]
	v_mfma_i32_16x16x64_i8 v[98:101], v[176:179], v[192:195], v[98:101]
	v_mfma_i32_16x16x64_i8 v[86:89], v[160:163], v[200:203], v[86:89]
	v_mfma_i32_16x16x64_i8 v[82:85], v[176:179], v[200:203], v[82:85]
	v_mfma_i32_16x16x64_i8 v[70:73], v[160:163], v[208:211], v[70:73]
	v_mfma_i32_16x16x64_i8 v[66:69], v[176:179], v[208:211], v[66:69]
	v_mfma_i32_16x16x64_i8 v[134:137], v[172:175], v[188:191], v[134:137]
	v_mfma_i32_16x16x64_i8 v[130:133], v[180:183], v[188:191], v[130:133]
	v_mfma_i32_16x16x64_i8 v[102:105], v[172:175], v[196:199], v[102:105]
	v_mfma_i32_16x16x64_i8 v[98:101], v[180:183], v[196:199], v[98:101]
	v_mfma_i32_16x16x64_i8 v[86:89], v[172:175], v[204:207], v[86:89]
	v_mfma_i32_16x16x64_i8 v[82:85], v[180:183], v[204:207], v[82:85]
	v_mfma_i32_16x16x64_i8 v[70:73], v[172:175], v[212:215], v[70:73]
	v_mfma_i32_16x16x64_i8 v[66:69], v[180:183], v[212:215], v[66:69]
	s_setprio 0
	s_barrier
	s_add_i32 s16, s18, s35
	v_lshl_add_u64 v[216:217], v[216:217], 0, s[44:45]
	s_mov_b32 m0, s16
	ds_read_b128 v[184:187], v170 offset:49152
	ds_read_b128 v[188:191], v170 offset:50176
	ds_read_b128 v[192:195], v170 offset:51200
	ds_read_b128 v[196:199], v170 offset:52224
	ds_read_b128 v[200:203], v170 offset:53248
	ds_read_b128 v[204:207], v170 offset:54272
	ds_read_b128 v[208:211], v170 offset:55296
	ds_read_b128 v[212:215], v170 offset:56320
	global_load_lds_dwordx4 v[216:217], off
	s_add_i32 m0, s16, 0x2000
	s_add_u32 s16, s82, 0x158080
	v_lshl_add_u64 v[216:217], v[218:219], 0, s[44:45]
	s_addc_u32 s17, s83, 0
	s_add_i32 s18, s19, s35
	global_load_lds_dwordx4 v[216:217], off
	v_lshl_add_u64 v[216:217], s[16:17], 0, v[148:149]
	s_mov_b32 m0, s18
	s_nop 0
	global_load_lds_dwordx4 v[216:217], off
	v_lshl_add_u64 v[216:217], s[16:17], 0, v[152:153]
	s_add_i32 m0, s18, 0x2000
	s_nop 0
	global_load_lds_dwordx4 v[216:217], off
	v_lshl_add_u64 v[216:217], v[220:221], 0, s[44:45]
	s_mov_b32 m0, s61
	s_nop 0
	global_load_lds_dwordx4 v[216:217], off
	v_lshl_add_u64 v[216:217], v[222:223], 0, s[44:45]
	s_mov_b32 m0, s66
	s_nop 0
	global_load_lds_dwordx4 v[216:217], off
	s_waitcnt vmcnt(8)
	s_waitcnt lgkmcnt(0)
	s_barrier
	s_setprio 1
	s_waitcnt lgkmcnt(0)
	v_mfma_i32_16x16x64_i8 v[62:65], v[106:109], v[184:187], v[62:65]
	v_mfma_i32_16x16x64_i8 v[58:61], v[114:117], v[184:187], v[58:61]
	v_mfma_i32_16x16x64_i8 v[46:49], v[106:109], v[192:195], v[46:49]
	v_mfma_i32_16x16x64_i8 v[42:45], v[114:117], v[192:195], v[42:45]
	v_mfma_i32_16x16x64_i8 v[30:33], v[106:109], v[200:203], v[30:33]
	v_mfma_i32_16x16x64_i8 v[26:29], v[114:117], v[200:203], v[26:29]
	v_mfma_i32_16x16x64_i8 v[14:17], v[106:109], v[208:211], v[14:17]
	v_mfma_i32_16x16x64_i8 v[10:13], v[114:117], v[208:211], v[10:13]
	v_mfma_i32_16x16x64_i8 v[62:65], v[110:113], v[188:191], v[62:65]
	v_mfma_i32_16x16x64_i8 v[58:61], v[122:125], v[188:191], v[58:61]
	v_mfma_i32_16x16x64_i8 v[46:49], v[110:113], v[196:199], v[46:49]
	v_mfma_i32_16x16x64_i8 v[42:45], v[122:125], v[196:199], v[42:45]
	v_mfma_i32_16x16x64_i8 v[30:33], v[110:113], v[204:207], v[30:33]
	v_mfma_i32_16x16x64_i8 v[26:29], v[122:125], v[204:207], v[26:29]
	v_mfma_i32_16x16x64_i8 v[14:17], v[110:113], v[212:215], v[14:17]
	v_mfma_i32_16x16x64_i8 v[10:13], v[122:125], v[212:215], v[10:13]
	s_setprio 0
	s_setprio 1
	v_mfma_i32_16x16x64_i8 v[54:57], v[160:163], v[184:187], v[54:57]
	v_mfma_i32_16x16x64_i8 v[50:53], v[176:179], v[184:187], v[50:53]
	v_mfma_i32_16x16x64_i8 v[38:41], v[160:163], v[192:195], v[38:41]
	v_mfma_i32_16x16x64_i8 v[34:37], v[176:179], v[192:195], v[34:37]
	v_mfma_i32_16x16x64_i8 v[22:25], v[160:163], v[200:203], v[22:25]
	v_mfma_i32_16x16x64_i8 v[18:21], v[176:179], v[200:203], v[18:21]
	v_mfma_i32_16x16x64_i8 v[6:9], v[160:163], v[208:211], v[6:9]
	v_mfma_i32_16x16x64_i8 v[2:5], v[176:179], v[208:211], v[2:5]
	v_mfma_i32_16x16x64_i8 v[54:57], v[172:175], v[188:191], v[54:57]
	v_mfma_i32_16x16x64_i8 v[50:53], v[180:183], v[188:191], v[50:53]
	v_mfma_i32_16x16x64_i8 v[38:41], v[172:175], v[196:199], v[38:41]
	v_mfma_i32_16x16x64_i8 v[34:37], v[180:183], v[196:199], v[34:37]
	v_mfma_i32_16x16x64_i8 v[22:25], v[172:175], v[204:207], v[22:25]
	v_mfma_i32_16x16x64_i8 v[18:21], v[180:183], v[204:207], v[18:21]
	v_mfma_i32_16x16x64_i8 v[6:9], v[172:175], v[212:215], v[6:9]
	v_mfma_i32_16x16x64_i8 v[2:5], v[180:183], v[212:215], v[2:5]
	s_setprio 0
	s_barrier
	s_add_i32 s13, s13, 2
	s_add_u32 s6, s6, 0x100
	s_addc_u32 s7, s7, 0
	s_add_u32 s8, s8, 0x100
	s_addc_u32 s12, s12, 0
	s_cmpk_gt_u32 s13, 0x53
	s_cbranch_scc0 .LBB0_362
	s_and_b64 vcc, exec, s[46:47]
	s_cbranch_vccz .LBB0_365
.LBB0_365:
	v_lshl_or_b32 v160, s92, 8, v167
	v_ashrrev_i32_e32 v161, 31, v160
	v_lshl_add_u64 v[110:111], v[160:161], 2, s[40:41]
	global_load_dwordx4 v[114:117], v[110:111], off offset:16
	global_load_dwordx4 v[122:125], v[110:111], off
	global_load_dwordx4 v[106:109], v[110:111], off offset:528
	s_nop 0
	global_load_dwordx4 v[110:113], v[110:111], off offset:512
	v_lshl_add_u32 v162, s91, 8, v1
	v_cndmask_b32_e64 v166, 0, 1, s[48:49]
	v_ashrrev_i32_e32 v163, 31, v162
	v_mov_b32_e32 v164, 0x39010204
	v_cmp_ne_u32_e64 s[6:7], 1, v166
	s_andn2_b64 vcc, exec, s[48:49]
	v_mov_b32_e32 v166, 0x39010204
	s_cbranch_vccnz .LBB0_367
	v_lshl_add_u64 v[172:173], v[162:163], 2, s[70:71]
	global_load_dword v166, v[172:173], off
	global_load_dword v200, v[172:173], off offset:64
	global_load_dword v201, v[172:173], off offset:128
	global_load_dword v202, v[172:173], off offset:192
	global_load_dword v203, v[172:173], off offset:512
	global_load_dword v204, v[172:173], off offset:576
	global_load_dword v205, v[172:173], off offset:640
	global_load_dword v206, v[172:173], off offset:704
	s_waitcnt vmcnt(0)
	v_mul_f32_e32 v166, 0x39010204, v166
.LBB0_367:
	v_cvt_f32_i32_e32 v143, v143
	v_cvt_f32_i32_e32 v145, v145
	v_cvt_f32_i32_e32 v144, v144
	v_cvt_f32_i32_e32 v142, v142
	v_cvt_f32_i32_e32 v141, v141
	v_cvt_f32_i32_e32 v139, v139
	v_cvt_f32_i32_e32 v138, v138
	v_cvt_f32_i32_e32 v140, v140
	v_cvt_f32_i32_e32 v135, v135
	v_cvt_f32_i32_e32 v134, v134
	v_cvt_f32_i32_e32 v133, v133
	v_cvt_f32_i32_e32 v131, v131
	v_cvt_f32_i32_e32 v130, v130
	v_cvt_f32_i32_e32 v132, v132
	v_cvt_f32_i32_e32 v137, v137
	v_cvt_f32_i32_e32 v136, v136
	v_lshlrev_b64 v[172:173], 13, v[162:163]
	v_lshl_add_u64 v[172:173], s[36:37], 0, v[172:173]
	s_waitcnt vmcnt(0)
	s_and_b64 vcc, exec, s[46:47]
	s_cbranch_vccz .Lalign_p3
	s_barrier
.Lalign_p3:
	v_pk_mul_f32 v[144:145], v[124:125], v[144:145]
	v_pk_mul_f32 v[142:143], v[122:123], v[142:143]
	v_pk_mul_f32 v[138:139], v[114:115], v[138:139]
	v_pk_mul_f32 v[140:141], v[116:117], v[140:141]
	v_lshl_add_u64 v[172:173], v[160:161], 1, v[172:173]
	v_pk_mul_f32 v[144:145], v[144:145], v[166:167] op_sel_hi:[1,0]
	v_pk_mul_f32 v[142:143], v[142:143], v[166:167] op_sel_hi:[1,0]
	v_pk_mul_f32 v[174:175], v[140:141], v[166:167] op_sel_hi:[1,0]
	v_pk_mul_f32 v[140:141], v[138:139], v[166:167] op_sel_hi:[1,0]
	v_cvt_pk_bf16_f32 v138, v142, v143
	v_cvt_pk_bf16_f32 v139, v144, v145
	v_pk_mul_f32 v[134:135], v[110:111], v[134:135]
	v_pk_mul_f32 v[130:131], v[106:107], v[130:131]
	v_pk_mul_f32 v[132:133], v[108:109], v[132:133]
	v_cvt_pk_bf16_f32 v140, v140, v141
	v_cvt_pk_bf16_f32 v141, v174, v175
	global_store_dwordx4 v[172:173], v[138:141], off
	v_pk_mul_f32 v[136:137], v[112:113], v[136:137]
	v_pk_mul_f32 v[134:135], v[134:135], v[166:167] op_sel_hi:[1,0]
	v_pk_mul_f32 v[138:139], v[132:133], v[166:167] op_sel_hi:[1,0]
	v_pk_mul_f32 v[132:133], v[130:131], v[166:167] op_sel_hi:[1,0]
	v_cvt_pk_bf16_f32 v130, v134, v135
	v_pk_mul_f32 v[136:137], v[136:137], v[166:167] op_sel_hi:[1,0]
	s_and_b64 vcc, exec, s[6:7]
	v_cvt_pk_bf16_f32 v131, v136, v137
	v_cvt_pk_bf16_f32 v132, v132, v133
	v_cvt_pk_bf16_f32 v133, v138, v139
	global_store_dwordx4 v[172:173], v[130:133], off offset:256
	s_nop 1
	v_or_b32_e32 v130, 16, v162
	v_ashrrev_i32_e32 v131, 31, v130
	s_cbranch_vccnz .LBB0_369
	v_mul_f32_e32 v164, 0x39010204, v200

.LBB0_541:
	ds_read_b128 v[146:149], v154
	ds_read_b128 v[158:161], v154 offset:1024
	ds_read_b128 v[162:165], v154 offset:2048
	ds_read_b128 v[166:169], v154 offset:3072
	ds_read_b128 v[170:173], v155
	ds_read_b128 v[174:177], v155 offset:1024
	ds_read_b128 v[178:181], v155 offset:2048
	ds_read_b128 v[182:185], v155 offset:3072
	s_add_u32 s18, s84, 0xfff00080
	s_addc_u32 s19, s85, -1
	s_cmp_eq_u32 s17, 60
	s_cselect_b32 s89, s5, s19
	s_cselect_b32 s88, s8, s18
	s_cselect_b32 s87, s9, s16
	s_cselect_b32 s86, s12, s13
	v_lshl_add_u64 v[218:219], s[84:85], 0, v[138:139]
	s_add_i32 m0, s56, 0xc000
	ds_read_b128 v[186:189], v156
	ds_read_b128 v[190:193], v156 offset:1024
	ds_read_b128 v[194:197], v156 offset:2048
	ds_read_b128 v[198:201], v156 offset:3072
	ds_read_b128 v[202:205], v156 offset:4096
	ds_read_b128 v[206:209], v156 offset:5120
	ds_read_b128 v[210:213], v156 offset:6144
	ds_read_b128 v[214:217], v156 offset:7168
	global_load_lds_dwordx4 v[218:219], off
	v_lshl_add_u64 v[218:219], s[84:85], 0, v[140:141]
	s_add_i32 m0, s56, 0xe000
	s_nop 0
	global_load_lds_dwordx4 v[218:219], off
	s_waitcnt vmcnt(8)
	s_waitcnt lgkmcnt(0)
	s_barrier
	s_setprio 1
	s_waitcnt lgkmcnt(0)
	v_mfma_f32_16x16x32_bf16 v[126:129], v[146:149], v[186:189], v[126:129]
	v_mfma_f32_16x16x32_bf16 v[122:125], v[162:165], v[186:189], v[122:125]
	v_mfma_f32_16x16x32_bf16 v[110:113], v[146:149], v[194:197], v[110:113]
	v_mfma_f32_16x16x32_bf16 v[106:109], v[162:165], v[194:197], v[106:109]
	v_mfma_f32_16x16x32_bf16 v[94:97], v[146:149], v[202:205], v[94:97]
	v_mfma_f32_16x16x32_bf16 v[90:93], v[162:165], v[202:205], v[90:93]
	v_mfma_f32_16x16x32_bf16 v[78:81], v[146:149], v[210:213], v[78:81]
	v_mfma_f32_16x16x32_bf16 v[74:77], v[162:165], v[210:213], v[74:77]
	v_mfma_f32_16x16x32_bf16 v[126:129], v[158:161], v[190:193], v[126:129]
	v_mfma_f32_16x16x32_bf16 v[122:125], v[166:169], v[190:193], v[122:125]
	v_mfma_f32_16x16x32_bf16 v[110:113], v[158:161], v[198:201], v[110:113]
	v_mfma_f32_16x16x32_bf16 v[106:109], v[166:169], v[198:201], v[106:109]
	v_mfma_f32_16x16x32_bf16 v[94:97], v[158:161], v[206:209], v[94:97]
	v_mfma_f32_16x16x32_bf16 v[90:93], v[166:169], v[206:209], v[90:93]
	v_mfma_f32_16x16x32_bf16 v[78:81], v[158:161], v[214:217], v[78:81]
	v_mfma_f32_16x16x32_bf16 v[74:77], v[166:169], v[214:217], v[74:77]
	s_setprio 0
	s_setprio 1
	v_mfma_f32_16x16x32_bf16 v[118:121], v[170:173], v[186:189], v[118:121]
	v_mfma_f32_16x16x32_bf16 v[114:117], v[178:181], v[186:189], v[114:117]
	v_mfma_f32_16x16x32_bf16 v[102:105], v[170:173], v[194:197], v[102:105]
	v_mfma_f32_16x16x32_bf16 v[98:101], v[178:181], v[194:197], v[98:101]
	v_mfma_f32_16x16x32_bf16 v[86:89], v[170:173], v[202:205], v[86:89]
	v_mfma_f32_16x16x32_bf16 v[82:85], v[178:181], v[202:205], v[82:85]
	v_mfma_f32_16x16x32_bf16 v[70:73], v[170:173], v[210:213], v[70:73]
	v_mfma_f32_16x16x32_bf16 v[66:69], v[178:181], v[210:213], v[66:69]
	v_mfma_f32_16x16x32_bf16 v[118:121], v[174:177], v[190:193], v[118:121]
	v_mfma_f32_16x16x32_bf16 v[114:117], v[182:185], v[190:193], v[114:117]
	v_mfma_f32_16x16x32_bf16 v[102:105], v[174:177], v[198:201], v[102:105]
	v_mfma_f32_16x16x32_bf16 v[98:101], v[182:185], v[198:201], v[98:101]
	v_mfma_f32_16x16x32_bf16 v[86:89], v[174:177], v[206:209], v[86:89]
	v_mfma_f32_16x16x32_bf16 v[82:85], v[182:185], v[206:209], v[82:85]
	v_mfma_f32_16x16x32_bf16 v[70:73], v[174:177], v[214:217], v[70:73]
	v_mfma_f32_16x16x32_bf16 v[66:69], v[182:185], v[214:217], v[66:69]
	s_setprio 0
	s_barrier
	s_add_i32 s18, s83, s35
	v_lshl_add_u64 v[218:219], s[86:87], 0, v[132:133]
	s_mov_b32 m0, s18
	ds_read_b128 v[186:189], v156 offset:16384
	ds_read_b128 v[190:193], v156 offset:17408
	ds_read_b128 v[194:197], v156 offset:18432
	ds_read_b128 v[198:201], v156 offset:19456
	ds_read_b128 v[202:205], v156 offset:20480
	ds_read_b128 v[206:209], v156 offset:21504
	ds_read_b128 v[210:213], v156 offset:22528
	ds_read_b128 v[214:217], v156 offset:23552
	global_load_lds_dwordx4 v[218:219], off
	s_add_i32 m0, s18, 0x2000
	s_add_u32 s18, s86, 0x100000
	v_lshl_add_u64 v[220:221], s[86:87], 0, v[136:137]
	s_addc_u32 s19, s87, 0
	s_add_i32 s20, s90, s35
	global_load_lds_dwordx4 v[220:221], off
	v_lshl_add_u64 v[222:223], s[18:19], 0, v[132:133]
	s_mov_b32 m0, s20
	v_lshl_add_u64 v[224:225], s[88:89], 0, v[134:135]
	global_load_lds_dwordx4 v[222:223], off
	v_lshl_add_u64 v[222:223], s[18:19], 0, v[136:137]
	s_add_i32 m0, s20, 0x2000
	s_nop 0
	global_load_lds_dwordx4 v[222:223], off
	v_lshl_add_u64 v[222:223], s[88:89], 0, v[130:131]
	s_mov_b32 m0, s56
	s_nop 0
	global_load_lds_dwordx4 v[222:223], off
	s_mov_b32 m0, s57
	s_nop 0
	global_load_lds_dwordx4 v[224:225], off
	s_waitcnt vmcnt(8)
	s_waitcnt lgkmcnt(0)
	s_barrier
	s_setprio 1
	s_waitcnt lgkmcnt(0)
	v_mfma_f32_16x16x32_bf16 v[62:65], v[146:149], v[186:189], v[62:65]
	v_mfma_f32_16x16x32_bf16 v[58:61], v[162:165], v[186:189], v[58:61]
	v_mfma_f32_16x16x32_bf16 v[46:49], v[146:149], v[194:197], v[46:49]
	v_mfma_f32_16x16x32_bf16 v[42:45], v[162:165], v[194:197], v[42:45]
	v_mfma_f32_16x16x32_bf16 v[30:33], v[146:149], v[202:205], v[30:33]
	v_mfma_f32_16x16x32_bf16 v[26:29], v[162:165], v[202:205], v[26:29]
	v_mfma_f32_16x16x32_bf16 v[14:17], v[146:149], v[210:213], v[14:17]
	v_mfma_f32_16x16x32_bf16 v[10:13], v[162:165], v[210:213], v[10:13]
	v_mfma_f32_16x16x32_bf16 v[62:65], v[158:161], v[190:193], v[62:65]
	v_mfma_f32_16x16x32_bf16 v[58:61], v[166:169], v[190:193], v[58:61]
	v_mfma_f32_16x16x32_bf16 v[46:49], v[158:161], v[198:201], v[46:49]
	v_mfma_f32_16x16x32_bf16 v[42:45], v[166:169], v[198:201], v[42:45]
	v_mfma_f32_16x16x32_bf16 v[30:33], v[158:161], v[206:209], v[30:33]
	v_mfma_f32_16x16x32_bf16 v[26:29], v[166:169], v[206:209], v[26:29]
	v_mfma_f32_16x16x32_bf16 v[14:17], v[158:161], v[214:217], v[14:17]
	v_mfma_f32_16x16x32_bf16 v[10:13], v[166:169], v[214:217], v[10:13]
	s_setprio 0
	s_setprio 1
	v_mfma_f32_16x16x32_bf16 v[54:57], v[170:173], v[186:189], v[54:57]
	v_mfma_f32_16x16x32_bf16 v[50:53], v[178:181], v[186:189], v[50:53]
	v_mfma_f32_16x16x32_bf16 v[38:41], v[170:173], v[194:197], v[38:41]
	v_mfma_f32_16x16x32_bf16 v[34:37], v[178:181], v[194:197], v[34:37]
	v_mfma_f32_16x16x32_bf16 v[22:25], v[170:173], v[202:205], v[22:25]
	v_mfma_f32_16x16x32_bf16 v[18:21], v[178:181], v[202:205], v[18:21]
	v_mfma_f32_16x16x32_bf16 v[6:9], v[170:173], v[210:213], v[6:9]
	v_mfma_f32_16x16x32_bf16 v[2:5], v[178:181], v[210:213], v[2:5]
	v_mfma_f32_16x16x32_bf16 v[54:57], v[174:177], v[190:193], v[54:57]
	v_mfma_f32_16x16x32_bf16 v[50:53], v[182:185], v[190:193], v[50:53]
	v_mfma_f32_16x16x32_bf16 v[38:41], v[174:177], v[198:201], v[38:41]
	v_mfma_f32_16x16x32_bf16 v[34:37], v[182:185], v[198:201], v[34:37]
	v_mfma_f32_16x16x32_bf16 v[22:25], v[174:177], v[206:209], v[22:25]
	v_mfma_f32_16x16x32_bf16 v[18:21], v[182:185], v[206:209], v[18:21]
	v_mfma_f32_16x16x32_bf16 v[6:9], v[174:177], v[214:217], v[6:9]
	v_mfma_f32_16x16x32_bf16 v[2:5], v[182:185], v[214:217], v[2:5]
	s_setprio 0
	s_barrier
	s_add_i32 s20, 0, 0x18000
	v_add_u32_e32 v150, s20, v151
	s_add_i32 s21, 0, 0x1c000
	ds_read_b128 v[146:149], v150
	ds_read_b128 v[158:161], v150 offset:1024
	ds_read_b128 v[162:165], v150 offset:2048
	ds_read_b128 v[166:169], v150 offset:3072
	v_add_u32_e32 v150, s21, v151
	ds_read_b128 v[170:173], v150
	ds_read_b128 v[174:177], v150 offset:1024
	ds_read_b128 v[178:181], v150 offset:2048
	ds_read_b128 v[182:185], v150 offset:3072
	s_add_u32 s18, s88, 0x100000
	s_addc_u32 s19, s89, 0
	s_mov_b32 m0, s58
	v_lshl_add_u64 v[228:229], s[18:19], 0, v[130:131]
	ds_read_b128 v[186:189], v156 offset:32768
	ds_read_b128 v[190:193], v156 offset:33792
	ds_read_b128 v[194:197], v156 offset:34816
	ds_read_b128 v[198:201], v156 offset:35840
	ds_read_b128 v[202:205], v156 offset:36864
	ds_read_b128 v[206:209], v156 offset:37888
	ds_read_b128 v[210:213], v156 offset:38912
	ds_read_b128 v[214:217], v156 offset:39936
	global_load_lds_dwordx4 v[228:229], off
	v_lshl_add_u64 v[228:229], s[18:19], 0, v[134:135]
	s_mov_b32 m0, s59
	s_nop 0
	global_load_lds_dwordx4 v[228:229], off
	s_waitcnt vmcnt(8)
	s_waitcnt lgkmcnt(0)
	s_barrier
	s_setprio 1
	s_waitcnt lgkmcnt(0)
	v_mfma_f32_16x16x32_bf16 v[126:129], v[146:149], v[186:189], v[126:129]
	v_mfma_f32_16x16x32_bf16 v[122:125], v[162:165], v[186:189], v[122:125]
	v_mfma_f32_16x16x32_bf16 v[110:113], v[146:149], v[194:197], v[110:113]
	v_mfma_f32_16x16x32_bf16 v[106:109], v[162:165], v[194:197], v[106:109]
	v_mfma_f32_16x16x32_bf16 v[94:97], v[146:149], v[202:205], v[94:97]
	v_mfma_f32_16x16x32_bf16 v[90:93], v[162:165], v[202:205], v[90:93]
	v_mfma_f32_16x16x32_bf16 v[78:81], v[146:149], v[210:213], v[78:81]
	v_mfma_f32_16x16x32_bf16 v[74:77], v[162:165], v[210:213], v[74:77]
	v_mfma_f32_16x16x32_bf16 v[126:129], v[158:161], v[190:193], v[126:129]
	v_mfma_f32_16x16x32_bf16 v[122:125], v[166:169], v[190:193], v[122:125]
	v_mfma_f32_16x16x32_bf16 v[110:113], v[158:161], v[198:201], v[110:113]
	v_mfma_f32_16x16x32_bf16 v[106:109], v[166:169], v[198:201], v[106:109]
	v_mfma_f32_16x16x32_bf16 v[94:97], v[158:161], v[206:209], v[94:97]
	v_mfma_f32_16x16x32_bf16 v[90:93], v[166:169], v[206:209], v[90:93]
	v_mfma_f32_16x16x32_bf16 v[78:81], v[158:161], v[214:217], v[78:81]
	v_mfma_f32_16x16x32_bf16 v[74:77], v[166:169], v[214:217], v[74:77]
	s_setprio 0
	s_setprio 1
	v_mfma_f32_16x16x32_bf16 v[118:121], v[170:173], v[186:189], v[118:121]
	v_mfma_f32_16x16x32_bf16 v[114:117], v[178:181], v[186:189], v[114:117]
	v_mfma_f32_16x16x32_bf16 v[102:105], v[170:173], v[194:197], v[102:105]
	v_mfma_f32_16x16x32_bf16 v[98:101], v[178:181], v[194:197], v[98:101]
	v_mfma_f32_16x16x32_bf16 v[86:89], v[170:173], v[202:205], v[86:89]
	v_mfma_f32_16x16x32_bf16 v[82:85], v[178:181], v[202:205], v[82:85]
	v_mfma_f32_16x16x32_bf16 v[70:73], v[170:173], v[210:213], v[70:73]
	v_mfma_f32_16x16x32_bf16 v[66:69], v[178:181], v[210:213], v[66:69]
	v_mfma_f32_16x16x32_bf16 v[118:121], v[174:177], v[190:193], v[118:121]
	v_mfma_f32_16x16x32_bf16 v[114:117], v[182:185], v[190:193], v[114:117]
	v_mfma_f32_16x16x32_bf16 v[102:105], v[174:177], v[198:201], v[102:105]
	v_mfma_f32_16x16x32_bf16 v[98:101], v[182:185], v[198:201], v[98:101]
	v_mfma_f32_16x16x32_bf16 v[86:89], v[174:177], v[206:209], v[86:89]
	v_mfma_f32_16x16x32_bf16 v[82:85], v[182:185], v[206:209], v[82:85]
	v_mfma_f32_16x16x32_bf16 v[70:73], v[174:177], v[214:217], v[70:73]
	v_mfma_f32_16x16x32_bf16 v[66:69], v[182:185], v[214:217], v[66:69]
	s_setprio 0
	s_barrier
	s_add_i32 s18, s20, s35
	v_lshl_add_u64 v[218:219], v[218:219], 0, s[40:41]
	s_mov_b32 m0, s18
	ds_read_b128 v[186:189], v156 offset:49152
	ds_read_b128 v[190:193], v156 offset:50176
	ds_read_b128 v[194:197], v156 offset:51200
	ds_read_b128 v[198:201], v156 offset:52224
	ds_read_b128 v[202:205], v156 offset:53248
	ds_read_b128 v[206:209], v156 offset:54272
	ds_read_b128 v[210:213], v156 offset:55296
	ds_read_b128 v[214:217], v156 offset:56320
	global_load_lds_dwordx4 v[218:219], off
	s_add_i32 m0, s18, 0x2000
	s_add_u32 s18, s86, 0x100080
	v_lshl_add_u64 v[218:219], v[220:221], 0, s[40:41]
	s_addc_u32 s19, s87, 0
	s_add_i32 s20, s21, s35
	global_load_lds_dwordx4 v[218:219], off
	v_lshl_add_u64 v[218:219], s[18:19], 0, v[132:133]
	s_mov_b32 m0, s20
	s_nop 0
	global_load_lds_dwordx4 v[218:219], off
	v_lshl_add_u64 v[218:219], s[18:19], 0, v[136:137]
	s_add_i32 m0, s20, 0x2000
	s_nop 0
	global_load_lds_dwordx4 v[218:219], off
	v_lshl_add_u64 v[218:219], v[222:223], 0, s[40:41]
	s_mov_b32 m0, s66
	s_nop 0
	global_load_lds_dwordx4 v[218:219], off
	v_lshl_add_u64 v[218:219], v[224:225], 0, s[40:41]
	s_mov_b32 m0, s67
	s_nop 0
	global_load_lds_dwordx4 v[218:219], off
	s_waitcnt vmcnt(8)
	s_waitcnt lgkmcnt(0)
	s_barrier
	s_setprio 1
	s_waitcnt lgkmcnt(0)
	v_mfma_f32_16x16x32_bf16 v[62:65], v[146:149], v[186:189], v[62:65]
	v_mfma_f32_16x16x32_bf16 v[58:61], v[162:165], v[186:189], v[58:61]
	v_mfma_f32_16x16x32_bf16 v[46:49], v[146:149], v[194:197], v[46:49]
	v_mfma_f32_16x16x32_bf16 v[42:45], v[162:165], v[194:197], v[42:45]
	v_mfma_f32_16x16x32_bf16 v[30:33], v[146:149], v[202:205], v[30:33]
	v_mfma_f32_16x16x32_bf16 v[26:29], v[162:165], v[202:205], v[26:29]
	v_mfma_f32_16x16x32_bf16 v[14:17], v[146:149], v[210:213], v[14:17]
	v_mfma_f32_16x16x32_bf16 v[10:13], v[162:165], v[210:213], v[10:13]
	v_mfma_f32_16x16x32_bf16 v[62:65], v[158:161], v[190:193], v[62:65]
	v_mfma_f32_16x16x32_bf16 v[58:61], v[166:169], v[190:193], v[58:61]
	v_mfma_f32_16x16x32_bf16 v[46:49], v[158:161], v[198:201], v[46:49]
	v_mfma_f32_16x16x32_bf16 v[42:45], v[166:169], v[198:201], v[42:45]
	v_mfma_f32_16x16x32_bf16 v[30:33], v[158:161], v[206:209], v[30:33]
	v_mfma_f32_16x16x32_bf16 v[26:29], v[166:169], v[206:209], v[26:29]
	v_mfma_f32_16x16x32_bf16 v[14:17], v[158:161], v[214:217], v[14:17]
	v_mfma_f32_16x16x32_bf16 v[10:13], v[166:169], v[214:217], v[10:13]
	s_setprio 0
	s_setprio 1
	v_mfma_f32_16x16x32_bf16 v[54:57], v[170:173], v[186:189], v[54:57]
	v_mfma_f32_16x16x32_bf16 v[50:53], v[178:181], v[186:189], v[50:53]
	v_mfma_f32_16x16x32_bf16 v[38:41], v[170:173], v[194:197], v[38:41]
	v_mfma_f32_16x16x32_bf16 v[34:37], v[178:181], v[194:197], v[34:37]
	v_mfma_f32_16x16x32_bf16 v[22:25], v[170:173], v[202:205], v[22:25]
	v_mfma_f32_16x16x32_bf16 v[18:21], v[178:181], v[202:205], v[18:21]
	v_mfma_f32_16x16x32_bf16 v[6:9], v[170:173], v[210:213], v[6:9]
	v_mfma_f32_16x16x32_bf16 v[2:5], v[178:181], v[210:213], v[2:5]
	v_mfma_f32_16x16x32_bf16 v[54:57], v[174:177], v[190:193], v[54:57]
	v_mfma_f32_16x16x32_bf16 v[50:53], v[182:185], v[190:193], v[50:53]
	v_mfma_f32_16x16x32_bf16 v[38:41], v[174:177], v[198:201], v[38:41]
	v_mfma_f32_16x16x32_bf16 v[34:37], v[182:185], v[198:201], v[34:37]
	v_mfma_f32_16x16x32_bf16 v[22:25], v[174:177], v[206:209], v[22:25]
	v_mfma_f32_16x16x32_bf16 v[18:21], v[182:185], v[206:209], v[18:21]
	v_mfma_f32_16x16x32_bf16 v[6:9], v[174:177], v[214:217], v[6:9]
	v_mfma_f32_16x16x32_bf16 v[2:5], v[182:185], v[214:217], v[2:5]
	s_setprio 0
	s_barrier
	s_add_i32 s17, s17, 2
	s_add_u32 s84, s84, 0x100
	s_addc_u32 s85, s85, 0
	s_add_u32 s13, s13, 0x100
	s_addc_u32 s16, s16, 0
	s_cmp_gt_u32 s17, 61
	s_cbranch_scc0 .LBB0_541
	s_and_b64 vcc, exec, s[42:43]
	s_cbranch_vccz .LBB0_544
.LBB0_544:
	v_lshl_add_u32 v146, s4, 8, v1
	v_cndmask_b32_e64 v148, 0, 1, s[44:45]
	v_ashrrev_i32_e32 v147, 31, v146
	v_mov_b32_e32 v150, 1.0
	v_cmp_ne_u32_e64 s[4:5], 1, v148
	s_andn2_b64 vcc, exec, s[44:45]
	v_mov_b32_e32 v152, 1.0
	s_cbranch_vccnz .LBB0_546
	v_lshl_add_u64 v[148:149], v[146:147], 2, s[70:71]
	global_load_dword v152, v[148:149], off
	global_load_dword v200, v[148:149], off offset:64
	global_load_dword v201, v[148:149], off offset:128
	global_load_dword v202, v[148:149], off offset:192
	global_load_dword v203, v[148:149], off offset:512
	global_load_dword v204, v[148:149], off offset:576
	global_load_dword v205, v[148:149], off offset:640
	global_load_dword v206, v[148:149], off offset:704
.LBB0_546:
	v_lshl_or_b32 v148, s82, 8, v153
	v_mov_b64_e32 v[158:159], s[38:39]
	v_ashrrev_i32_e32 v149, 31, v148
	v_mad_i64_i32 v[158:159], s[8:9], v146, s91, v[158:159]
	v_lshl_add_u64 v[158:159], v[148:149], 1, v[158:159]
	s_waitcnt vmcnt(0)
	s_and_b64 vcc, exec, s[42:43]
	s_cbranch_vccz .Lalign_p5
	s_barrier
.Lalign_p5:
	v_pk_mul_f32 v[128:129], v[128:129], v[152:153] op_sel_hi:[1,0]
	v_pk_mul_f32 v[126:127], v[126:127], v[152:153] op_sel_hi:[1,0]
	v_pk_mul_f32 v[160:161], v[124:125], v[152:153] op_sel_hi:[1,0]
	v_pk_mul_f32 v[124:125], v[122:123], v[152:153] op_sel_hi:[1,0]
	v_cvt_pk_bf16_f32 v122, v126, v127
	v_cvt_pk_bf16_f32 v123, v128, v129
	v_pk_mul_f32 v[118:119], v[118:119], v[152:153] op_sel_hi:[1,0]
	v_cvt_pk_bf16_f32 v124, v124, v125
	v_cvt_pk_bf16_f32 v125, v160, v161
	global_store_dwordx4 v[158:159], v[122:125], off
	v_pk_mul_f32 v[120:121], v[120:121], v[152:153] op_sel_hi:[1,0]
	s_and_b64 vcc, exec, s[4:5]
	v_pk_mul_f32 v[122:123], v[116:117], v[152:153] op_sel_hi:[1,0]
	v_pk_mul_f32 v[116:117], v[114:115], v[152:153] op_sel_hi:[1,0]
	v_cvt_pk_bf16_f32 v114, v118, v119
	v_cvt_pk_bf16_f32 v115, v120, v121
	s_nop 0
	v_cvt_pk_bf16_f32 v116, v116, v117
	v_cvt_pk_bf16_f32 v117, v122, v123
	global_store_dwordx4 v[158:159], v[114:117], off offset:256
	s_nop 1
	v_or_b32_e32 v114, 16, v146
	v_ashrrev_i32_e32 v115, 31, v114
	s_cbranch_vccnz .LBB0_548
	v_mov_b32_e32 v150, v200

.LBB0_1018:
	v_lshl_or_b32 v172, s59, 7, v155
	v_ashrrev_i32_e32 v173, 31, v172
	v_lshlrev_b64 v[146:147], 2, v[172:173]
	v_lshl_add_u64 v[152:153], s[6:7], 0, v[146:147]
	v_lshl_add_u64 v[146:147], s[16:17], 0, v[146:147]
	global_load_dwordx4 v[148:151], v[152:153], off
	global_load_dwordx4 v[160:163], v[152:153], off offset:16
	global_load_dwordx4 v[164:167], v[146:147], off
	global_load_dwordx4 v[168:171], v[146:147], off offset:16
	v_lshl_add_u32 v146, s40, 8, v1
	v_ashrrev_i32_e32 v147, 31, v146
	v_lshl_add_u64 v[152:153], v[146:147], 2, s[70:71]
	global_load_dword v174, v[152:153], off
	global_load_dword v192, v[152:153], off offset:64
	global_load_dword v193, v[152:153], off offset:128
	global_load_dword v194, v[152:153], off offset:192
	global_load_dword v195, v[152:153], off offset:512
	global_load_dword v196, v[152:153], off offset:576
	global_load_dword v197, v[152:153], off offset:640
	global_load_dword v198, v[152:153], off offset:704
	v_cvt_f32_i32_e32 v177, v127
	v_cvt_f32_i32_e32 v176, v126
	v_cvt_f32_i32_e32 v185, v119
	v_cvt_f32_i32_e32 v184, v118
	v_cvt_f32_i32_e32 v179, v129
	v_cvt_f32_i32_e32 v178, v128
	v_cvt_f32_i32_e32 v187, v121
	v_cvt_f32_i32_e32 v186, v120
	v_cvt_f32_i32_e32 v189, v115
	v_cvt_f32_i32_e32 v188, v114
	v_mov_b64_e32 v[114:115], s[38:39]
	v_cvt_f32_i32_e32 v191, v117
	v_cvt_f32_i32_e32 v190, v116
	v_mad_i64_i32 v[118:119], s[8:9], v146, s58, v[114:115]
	v_lshlrev_b64 v[116:117], 1, v[172:173]
	v_cvt_f32_i32_e32 v181, v123
	v_cvt_f32_i32_e32 v180, v122
	v_lshl_add_u64 v[172:173], v[118:119], 0, v[116:117]
	v_cvt_f32_i32_e32 v183, v125
	v_cvt_f32_i32_e32 v182, v124
	v_cvt_f32_i32_e32 v111, v111
	v_cvt_f32_i32_e32 v110, v110
	v_cvt_f32_i32_e32 v103, v103
	v_cvt_f32_i32_e32 v102, v102
	v_cvt_f32_i32_e32 v113, v113
	v_cvt_f32_i32_e32 v112, v112
	v_cvt_f32_i32_e32 v107, v107
	v_cvt_f32_i32_e32 v106, v106
	v_cvt_f32_i32_e32 v99, v99
	v_cvt_f32_i32_e32 v98, v98
	v_cvt_f32_i32_e32 v101, v101
	v_cvt_f32_i32_e32 v100, v100
	v_cvt_f32_i32_e32 v109, v109
	v_cvt_f32_i32_e32 v108, v108
	v_cvt_f32_i32_e32 v105, v105
	v_cvt_f32_i32_e32 v104, v104
	v_cvt_f32_i32_e32 v95, v95
	v_cvt_f32_i32_e32 v94, v94
	v_cvt_f32_i32_e32 v87, v87
	v_cvt_f32_i32_e32 v86, v86
	v_cvt_f32_i32_e32 v97, v97
	v_cvt_f32_i32_e32 v96, v96
	v_cvt_f32_i32_e32 v91, v91
	v_cvt_f32_i32_e32 v90, v90
	v_cvt_f32_i32_e32 v83, v83
	v_cvt_f32_i32_e32 v82, v82
	v_cvt_f32_i32_e32 v85, v85
	v_cvt_f32_i32_e32 v84, v84
	v_cvt_f32_i32_e32 v93, v93
	v_cvt_f32_i32_e32 v92, v92
	v_cvt_f32_i32_e32 v89, v89
	v_cvt_f32_i32_e32 v88, v88
	v_cvt_f32_i32_e32 v79, v79
	v_cvt_f32_i32_e32 v78, v78
	v_cvt_f32_i32_e32 v81, v81
	v_cvt_f32_i32_e32 v80, v80
	v_cvt_f32_i32_e32 v71, v71
	v_cvt_f32_i32_e32 v70, v70
	v_cvt_f32_i32_e32 v75, v75
	v_cvt_f32_i32_e32 v74, v74
	v_cvt_f32_i32_e32 v67, v67
	v_cvt_f32_i32_e32 v66, v66
	v_cvt_f32_i32_e32 v69, v69
	v_cvt_f32_i32_e32 v68, v68
	v_cvt_f32_i32_e32 v77, v77
	v_cvt_f32_i32_e32 v76, v76
	v_cvt_f32_i32_e32 v73, v73
	v_cvt_f32_i32_e32 v72, v72
	v_cvt_f32_i32_e32 v63, v63
	v_cvt_f32_i32_e32 v62, v62
	v_cvt_f32_i32_e32 v65, v65
	v_cvt_f32_i32_e32 v64, v64
	s_waitcnt vmcnt(0)
	s_and_b64 vcc, exec, s[12:13]
	s_cbranch_vccz .Lalign_p11
	s_barrier
.Lalign_p11:
	v_pk_mul_f32 v[120:121], v[148:149], s[18:19] op_sel_hi:[1,0]
	v_pk_mul_f32 v[128:129], v[164:165], s[18:19] op_sel_hi:[1,0]
	v_pk_mul_f32 v[118:119], v[150:151], s[18:19] op_sel_hi:[1,0]
	v_pk_mul_f32 v[122:123], v[162:163], s[18:19] op_sel_hi:[1,0]
	v_pk_mul_f32 v[126:127], v[166:167], s[18:19] op_sel_hi:[1,0]
	v_pk_mul_f32 v[148:149], v[170:171], s[18:19] op_sel_hi:[1,0]
	v_pk_mul_f32 v[162:163], v[120:121], v[176:177]
	v_pk_mul_f32 v[170:171], v[128:129], v[184:185]
	v_pk_mul_f32 v[124:125], v[160:161], s[18:19] op_sel_hi:[1,0]
	v_pk_mul_f32 v[150:151], v[168:169], s[18:19] op_sel_hi:[1,0]
	v_pk_mul_f32 v[160:161], v[118:119], v[178:179]
	v_pk_mul_f32 v[168:169], v[126:127], v[186:187]
	v_pk_mul_f32 v[162:163], v[162:163], v[174:175] op_sel_hi:[1,0]
	v_pk_mul_f32 v[170:171], v[170:171], v[174:175] op_sel_hi:[1,0]
	v_pk_mul_f32 v[160:161], v[160:161], v[174:175] op_sel_hi:[1,0]
	v_pk_mul_f32 v[168:169], v[168:169], v[174:175] op_sel_hi:[1,0]
	v_mul_f32_e32 v147, v162, v170
	v_mul_f32_e32 v159, 0xbfb8aa3b, v162
	v_mul_f32_e32 v162, v163, v171
	v_mul_f32_e32 v163, 0xbfb8aa3b, v163
	v_mul_f32_e32 v168, v160, v168
	v_mul_f32_e32 v160, 0xbfb8aa3b, v160
	v_exp_f32_e32 v159, v159
	v_exp_f32_e32 v163, v163
	v_exp_f32_e32 v160, v160
	v_pk_mul_f32 v[164:165], v[122:123], v[182:183]
	v_pk_mul_f32 v[166:167], v[124:125], v[180:181]
	v_pk_mul_f32 v[176:177], v[148:149], v[190:191]
	v_pk_mul_f32 v[178:179], v[150:151], v[188:189]
	v_add_f32_e32 v159, 1.0, v159
	v_add_f32_e32 v163, 1.0, v163
	v_pk_mul_f32 v[164:165], v[164:165], v[174:175] op_sel_hi:[1,0]
	v_pk_mul_f32 v[166:167], v[166:167], v[174:175] op_sel_hi:[1,0]
	v_pk_mul_f32 v[176:177], v[176:177], v[174:175] op_sel_hi:[1,0]
	v_pk_mul_f32 v[174:175], v[178:179], v[174:175] op_sel_hi:[1,0]
	v_add_f32_e32 v160, 1.0, v160
	v_rcp_f32_e32 v159, v159
	v_rcp_f32_e32 v163, v163
	v_mul_f32_e32 v169, v161, v169
	v_mul_f32_e32 v161, 0xbfb8aa3b, v161
	v_mul_f32_e32 v170, v166, v174
	v_mul_f32_e32 v166, 0xbfb8aa3b, v166
	v_mul_f32_e32 v171, v167, v175
	v_mul_f32_e32 v167, 0xbfb8aa3b, v167
	v_rcp_f32_e32 v160, v160
	v_exp_f32_e32 v161, v161
	v_exp_f32_e32 v166, v166
	v_exp_f32_e32 v167, v167
	v_mul_f32_e32 v174, 0xbfb8aa3b, v164
	v_mul_f32_e32 v175, 0xbfb8aa3b, v165
	v_exp_f32_e32 v174, v174
	v_mul_f32_e32 v147, v147, v159
	v_mul_f32_e32 v159, v162, v163
	v_mul_f32_e32 v162, v168, v160
	v_cvt_pkrtz_f16_f32 v160, v147, v159
	v_exp_f32_e32 v147, v175
	v_add_f32_e32 v161, 1.0, v161
	v_add_f32_e32 v166, 1.0, v166
	v_add_f32_e32 v167, 1.0, v167
	v_rcp_f32_e32 v161, v161
	v_rcp_f32_e32 v166, v166
	v_rcp_f32_e32 v167, v167
	v_add_f32_e32 v159, 1.0, v174
	v_rcp_f32_e32 v159, v159
	v_add_f32_e32 v147, 1.0, v147
	v_rcp_f32_e32 v147, v147
	v_mul_f32_e32 v161, v169, v161
	v_mul_f32_e32 v163, v170, v166
	v_mul_f32_e32 v166, v171, v167
	v_cvt_pkrtz_f16_f32 v161, v162, v161
	v_cvt_pkrtz_f16_f32 v162, v163, v166
	v_mul_f32_e32 v163, v164, v176
	v_mul_f32_e32 v159, v163, v159
	v_mul_f32_e32 v163, v165, v177
	v_mul_f32_e32 v147, v163, v147
	v_cvt_pkrtz_f16_f32 v163, v159, v147
	global_store_dwordx4 v[172:173], v[160:163], off
	v_pk_mul_f32 v[110:111], v[120:121], v[110:111]
	v_pk_mul_f32 v[102:103], v[128:129], v[102:103]
	v_or_b32_e32 v160, 16, v146
	v_ashrrev_i32_e32 v161, 31, v160
	v_lshl_add_u64 v[162:163], v[160:161], 2, s[70:71]
	v_mov_b32_e32 v162, v192
	v_pk_mul_f32 v[112:113], v[118:119], v[112:113]
	v_pk_mul_f32 v[106:107], v[124:125], v[106:107]
	v_pk_mul_f32 v[100:101], v[148:149], v[100:101]
	v_pk_mul_f32 v[98:99], v[150:151], v[98:99]
	v_pk_mul_f32 v[108:109], v[122:123], v[108:109]
	v_pk_mul_f32 v[104:105], v[126:127], v[104:105]
	v_mad_i64_i32 v[160:161], s[8:9], v160, s58, v[114:115]
	v_lshl_add_u64 v[160:161], v[160:161], 0, v[116:117]
	v_pk_mul_f32 v[94:95], v[120:121], v[94:95]
	v_pk_mul_f32 v[86:87], v[128:129], v[86:87]
	v_pk_mul_f32 v[96:97], v[118:119], v[96:97]
	v_pk_mul_f32 v[90:91], v[124:125], v[90:91]
	v_pk_mul_f32 v[84:85], v[148:149], v[84:85]
	v_pk_mul_f32 v[82:83], v[150:151], v[82:83]
	v_pk_mul_f32 v[92:93], v[122:123], v[92:93]
	v_pk_mul_f32 v[88:89], v[126:127], v[88:89]
	v_pk_mul_f32 v[80:81], v[118:119], v[80:81]
	v_pk_mul_f32 v[78:79], v[120:121], v[78:79]
	v_pk_mul_f32 v[70:71], v[128:129], v[70:71]
	v_pk_mul_f32 v[74:75], v[124:125], v[74:75]
	v_pk_mul_f32 v[68:69], v[148:149], v[68:69]
	v_pk_mul_f32 v[66:67], v[150:151], v[66:67]
	v_pk_mul_f32 v[76:77], v[122:123], v[76:77]
	v_pk_mul_f32 v[72:73], v[126:127], v[72:73]
	v_cvt_f32_i32_e32 v59, v59
	v_cvt_f32_i32_e32 v58, v58
	v_cvt_f32_i32_e32 v61, v61
	v_cvt_f32_i32_e32 v60, v60
	v_cvt_f32_i32_e32 v55, v55
	v_cvt_f32_i32_e32 v54, v54
	v_cvt_f32_i32_e32 v57, v57
	v_cvt_f32_i32_e32 v56, v56
	v_cvt_f32_i32_e32 v51, v51
	v_cvt_f32_i32_e32 v50, v50
	v_cvt_f32_i32_e32 v53, v53
	v_cvt_f32_i32_e32 v52, v52
	v_pk_mul_f32 v[64:65], v[118:119], v[64:65]
	v_pk_mul_f32 v[62:63], v[120:121], v[62:63]
	v_pk_mul_f32 v[60:61], v[122:123], v[60:61]
	v_pk_mul_f32 v[58:59], v[124:125], v[58:59]
	v_pk_mul_f32 v[56:57], v[126:127], v[56:57]
	v_pk_mul_f32 v[54:55], v[128:129], v[54:55]
	v_pk_mul_f32 v[52:53], v[148:149], v[52:53]
	v_pk_mul_f32 v[50:51], v[150:151], v[50:51]
	v_cvt_f32_i32_e32 v47, v47
	v_cvt_f32_i32_e32 v46, v46
	v_cvt_f32_i32_e32 v49, v49
	v_cvt_f32_i32_e32 v48, v48
	v_cvt_f32_i32_e32 v43, v43
	v_cvt_f32_i32_e32 v42, v42
	v_cvt_f32_i32_e32 v45, v45
	v_cvt_f32_i32_e32 v44, v44
	v_cvt_f32_i32_e32 v39, v39
	v_cvt_f32_i32_e32 v38, v38
	v_cvt_f32_i32_e32 v41, v41
	v_cvt_f32_i32_e32 v40, v40
	v_cvt_f32_i32_e32 v35, v35
	v_cvt_f32_i32_e32 v34, v34
	v_cvt_f32_i32_e32 v37, v37
	v_cvt_f32_i32_e32 v36, v36
	v_pk_mul_f32 v[48:49], v[118:119], v[48:49]
	v_pk_mul_f32 v[46:47], v[120:121], v[46:47]
	v_pk_mul_f32 v[44:45], v[122:123], v[44:45]
	v_pk_mul_f32 v[42:43], v[124:125], v[42:43]
	v_pk_mul_f32 v[40:41], v[126:127], v[40:41]
	v_pk_mul_f32 v[38:39], v[128:129], v[38:39]
	v_pk_mul_f32 v[36:37], v[148:149], v[36:37]
	v_pk_mul_f32 v[34:35], v[150:151], v[34:35]
	v_cvt_f32_i32_e32 v31, v31
	v_cvt_f32_i32_e32 v30, v30
	v_cvt_f32_i32_e32 v33, v33
	v_cvt_f32_i32_e32 v32, v32
	v_cvt_f32_i32_e32 v27, v27
	v_cvt_f32_i32_e32 v26, v26
	v_cvt_f32_i32_e32 v29, v29
	v_cvt_f32_i32_e32 v28, v28
	v_cvt_f32_i32_e32 v23, v23
	v_cvt_f32_i32_e32 v22, v22
	v_pk_mul_f32 v[110:111], v[110:111], v[162:163] op_sel_hi:[1,0]
	v_pk_mul_f32 v[102:103], v[102:103], v[162:163] op_sel_hi:[1,0]
	v_pk_mul_f32 v[112:113], v[112:113], v[162:163] op_sel_hi:[1,0]
	v_pk_mul_f32 v[106:107], v[106:107], v[162:163] op_sel_hi:[1,0]
	v_pk_mul_f32 v[164:165], v[100:101], v[162:163] op_sel_hi:[1,0]
	v_pk_mul_f32 v[98:99], v[98:99], v[162:163] op_sel_hi:[1,0]
	v_mul_f32_e32 v100, v110, v102
	v_mul_f32_e32 v101, 0xbfb8aa3b, v110
	v_mul_f32_e32 v102, v111, v103
	v_mul_f32_e32 v103, 0xbfb8aa3b, v111
	v_mul_f32_e32 v110, 0xbfb8aa3b, v112
	v_mul_f32_e32 v111, 0xbfb8aa3b, v113
	v_mul_f32_e32 v98, v106, v98
	v_mul_f32_e32 v106, 0xbfb8aa3b, v106
	v_exp_f32_e32 v101, v101
	v_exp_f32_e32 v103, v103
	v_mul_f32_e32 v99, v107, v99
	v_mul_f32_e32 v107, 0xbfb8aa3b, v107
	v_exp_f32_e32 v110, v110
	v_exp_f32_e32 v111, v111
	v_exp_f32_e32 v106, v106
	v_exp_f32_e32 v107, v107
	v_pk_mul_f32 v[108:109], v[108:109], v[162:163] op_sel_hi:[1,0]
	v_pk_mul_f32 v[104:105], v[104:105], v[162:163] op_sel_hi:[1,0]
	v_add_f32_e32 v101, 1.0, v101
	v_add_f32_e32 v103, 1.0, v103
	v_mul_f32_e32 v104, v112, v104
	v_mul_f32_e32 v112, 0xbfb8aa3b, v108
	v_add_f32_e32 v110, 1.0, v110
	v_add_f32_e32 v111, 1.0, v111
	v_add_f32_e32 v106, 1.0, v106
	v_rcp_f32_e32 v101, v101
	v_rcp_f32_e32 v103, v103
	v_mul_f32_e32 v105, v113, v105
	v_mul_f32_e32 v113, 0xbfb8aa3b, v109
	v_exp_f32_e32 v112, v112
	v_add_f32_e32 v107, 1.0, v107
	v_rcp_f32_e32 v110, v110
	v_rcp_f32_e32 v111, v111
	v_rcp_f32_e32 v106, v106
	v_exp_f32_e32 v113, v113
	v_rcp_f32_e32 v107, v107
	v_mul_f32_e32 v100, v100, v101
	v_mul_f32_e32 v101, v102, v103
	v_mul_f32_e32 v102, v104, v110
	v_mul_f32_e32 v103, v105, v111
	v_mul_f32_e32 v104, v98, v106
	v_cvt_pkrtz_f16_f32 v98, v100, v101
	v_add_f32_e32 v101, 1.0, v112
	v_mul_f32_e32 v105, v99, v107
	v_cvt_pkrtz_f16_f32 v99, v102, v103
	v_rcp_f32_e32 v101, v101
	v_add_f32_e32 v102, 1.0, v113
	v_rcp_f32_e32 v102, v102
	v_mul_f32_e32 v103, v108, v164
	v_mul_f32_e32 v101, v103, v101
	v_mul_f32_e32 v103, v109, v165
	v_mul_f32_e32 v102, v103, v102
	v_cvt_pkrtz_f16_f32 v100, v104, v105
	v_cvt_pkrtz_f16_f32 v101, v101, v102
	global_store_dwordx4 v[160:161], v[98:101], off
	v_cvt_f32_i32_e32 v25, v25
	v_cvt_f32_i32_e32 v24, v24
	v_or_b32_e32 v98, 32, v146
	v_ashrrev_i32_e32 v99, 31, v98
	v_lshl_add_u64 v[100:101], v[98:99], 2, s[70:71]
	v_mov_b32_e32 v100, v193
	v_mad_i64_i32 v[98:99], s[8:9], v98, s58, v[114:115]
	v_lshl_add_u64 v[98:99], v[98:99], 0, v[116:117]
	v_cvt_f32_i32_e32 v19, v19
	v_cvt_f32_i32_e32 v18, v18
	v_cvt_f32_i32_e32 v21, v21
	v_cvt_f32_i32_e32 v20, v20
	v_pk_mul_f32 v[32:33], v[118:119], v[32:33]
	v_pk_mul_f32 v[30:31], v[120:121], v[30:31]
	v_pk_mul_f32 v[28:29], v[122:123], v[28:29]
	v_pk_mul_f32 v[26:27], v[124:125], v[26:27]
	v_pk_mul_f32 v[24:25], v[126:127], v[24:25]
	v_pk_mul_f32 v[22:23], v[128:129], v[22:23]
	v_pk_mul_f32 v[20:21], v[148:149], v[20:21]
	v_pk_mul_f32 v[18:19], v[150:151], v[18:19]
	v_cvt_f32_i32_e32 v15, v15
	v_cvt_f32_i32_e32 v14, v14
	v_cvt_f32_i32_e32 v17, v17
	v_cvt_f32_i32_e32 v16, v16
	v_cvt_f32_i32_e32 v11, v11
	v_cvt_f32_i32_e32 v10, v10
	v_cvt_f32_i32_e32 v13, v13
	v_cvt_f32_i32_e32 v12, v12
	v_cvt_f32_i32_e32 v7, v7
	v_cvt_f32_i32_e32 v6, v6
	v_cvt_f32_i32_e32 v9, v9
	v_cvt_f32_i32_e32 v8, v8
	v_cvt_f32_i32_e32 v3, v3
	v_cvt_f32_i32_e32 v2, v2
	v_cvt_f32_i32_e32 v5, v5
	v_cvt_f32_i32_e32 v4, v4
	v_pk_mul_f32 v[16:17], v[118:119], v[16:17]
	v_pk_mul_f32 v[14:15], v[120:121], v[14:15]
	v_pk_mul_f32 v[12:13], v[122:123], v[12:13]
	v_pk_mul_f32 v[10:11], v[124:125], v[10:11]
	v_pk_mul_f32 v[8:9], v[126:127], v[8:9]
	v_pk_mul_f32 v[6:7], v[128:129], v[6:7]
	v_pk_mul_f32 v[4:5], v[148:149], v[4:5]
	v_pk_mul_f32 v[2:3], v[150:151], v[2:3]
	s_andn2_b64 vcc, exec, s[2:3]
	s_mov_b64 s[2:3], -1
	v_pk_mul_f32 v[94:95], v[94:95], v[100:101] op_sel_hi:[1,0]
	v_pk_mul_f32 v[86:87], v[86:87], v[100:101] op_sel_hi:[1,0]
	v_pk_mul_f32 v[96:97], v[96:97], v[100:101] op_sel_hi:[1,0]
	v_pk_mul_f32 v[90:91], v[90:91], v[100:101] op_sel_hi:[1,0]
	v_pk_mul_f32 v[102:103], v[84:85], v[100:101] op_sel_hi:[1,0]
	v_pk_mul_f32 v[82:83], v[82:83], v[100:101] op_sel_hi:[1,0]
	v_mul_f32_e32 v84, v94, v86
	v_mul_f32_e32 v85, 0xbfb8aa3b, v94
	v_mul_f32_e32 v86, v95, v87
	v_mul_f32_e32 v87, 0xbfb8aa3b, v95
	v_mul_f32_e32 v94, 0xbfb8aa3b, v96
	v_mul_f32_e32 v82, v90, v82
	v_mul_f32_e32 v90, 0xbfb8aa3b, v90
	v_exp_f32_e32 v85, v85
	v_exp_f32_e32 v87, v87
	v_exp_f32_e32 v94, v94
	v_exp_f32_e32 v90, v90
	v_mul_f32_e32 v95, 0xbfb8aa3b, v97
	v_pk_mul_f32 v[92:93], v[92:93], v[100:101] op_sel_hi:[1,0]
	v_pk_mul_f32 v[88:89], v[88:89], v[100:101] op_sel_hi:[1,0]
	v_mul_f32_e32 v83, v91, v83
	v_mul_f32_e32 v91, 0xbfb8aa3b, v91
	v_exp_f32_e32 v95, v95
	v_add_f32_e32 v85, 1.0, v85
	v_add_f32_e32 v87, 1.0, v87
	v_mul_f32_e32 v88, v96, v88
	v_mul_f32_e32 v89, v97, v89
	v_mul_f32_e32 v96, 0xbfb8aa3b, v92
	v_mul_f32_e32 v97, 0xbfb8aa3b, v93
	v_exp_f32_e32 v91, v91
	v_add_f32_e32 v94, 1.0, v94
	v_add_f32_e32 v90, 1.0, v90
	v_rcp_f32_e32 v85, v85
	v_rcp_f32_e32 v87, v87
	v_exp_f32_e32 v96, v96
	v_exp_f32_e32 v97, v97
	v_rcp_f32_e32 v94, v94
	v_rcp_f32_e32 v90, v90
	v_add_f32_e32 v95, 1.0, v95
	v_add_f32_e32 v91, 1.0, v91
	v_rcp_f32_e32 v95, v95
	v_mul_f32_e32 v84, v84, v85
	v_mul_f32_e32 v85, v86, v87
	v_add_f32_e32 v96, 1.0, v96
	v_rcp_f32_e32 v91, v91
	v_mul_f32_e32 v86, v88, v94
	v_mul_f32_e32 v88, v82, v90
	v_cvt_pkrtz_f16_f32 v82, v84, v85
	v_add_f32_e32 v85, 1.0, v97
	v_rcp_f32_e32 v96, v96
	v_rcp_f32_e32 v85, v85
	v_mul_f32_e32 v87, v89, v95
	v_mul_f32_e32 v89, v83, v91
	v_cvt_pkrtz_f16_f32 v83, v86, v87
	v_mul_f32_e32 v86, v92, v102
	v_mul_f32_e32 v87, v93, v103
	v_mul_f32_e32 v86, v86, v96
	v_mul_f32_e32 v85, v87, v85
	v_cvt_pkrtz_f16_f32 v84, v88, v89
	v_cvt_pkrtz_f16_f32 v85, v86, v85
	global_store_dwordx4 v[98:99], v[82:85], off
	s_nop 1
	v_or_b32_e32 v82, 48, v146
	v_ashrrev_i32_e32 v83, 31, v82
	v_lshl_add_u64 v[84:85], v[82:83], 2, s[70:71]
	v_mov_b32_e32 v84, v194
	v_mad_i64_i32 v[82:83], s[8:9], v82, s58, v[114:115]
	v_lshl_add_u64 v[82:83], v[82:83], 0, v[116:117]
	v_pk_mul_f32 v[80:81], v[80:81], v[84:85] op_sel_hi:[1,0]
	v_pk_mul_f32 v[78:79], v[78:79], v[84:85] op_sel_hi:[1,0]
	v_pk_mul_f32 v[70:71], v[70:71], v[84:85] op_sel_hi:[1,0]
	v_pk_mul_f32 v[74:75], v[74:75], v[84:85] op_sel_hi:[1,0]
	v_pk_mul_f32 v[86:87], v[68:69], v[84:85] op_sel_hi:[1,0]
	v_pk_mul_f32 v[66:67], v[66:67], v[84:85] op_sel_hi:[1,0]
	v_mul_f32_e32 v68, v78, v70
	v_mul_f32_e32 v69, 0xbfb8aa3b, v78
	v_mul_f32_e32 v70, v79, v71
	v_mul_f32_e32 v71, 0xbfb8aa3b, v79
	v_mul_f32_e32 v78, 0xbfb8aa3b, v80
	v_mul_f32_e32 v79, 0xbfb8aa3b, v81
	v_pk_mul_f32 v[76:77], v[76:77], v[84:85] op_sel_hi:[1,0]
	v_pk_mul_f32 v[72:73], v[72:73], v[84:85] op_sel_hi:[1,0]
	v_mul_f32_e32 v66, v74, v66
	v_mul_f32_e32 v74, 0xbfb8aa3b, v74
	v_mul_f32_e32 v67, v75, v67
	v_mul_f32_e32 v75, 0xbfb8aa3b, v75
	v_exp_f32_e32 v69, v69
	v_exp_f32_e32 v71, v71
	v_exp_f32_e32 v78, v78
	v_exp_f32_e32 v79, v79
	v_mul_f32_e32 v72, v80, v72
	v_mul_f32_e32 v73, v81, v73
	v_mul_f32_e32 v80, 0xbfb8aa3b, v76
	v_mul_f32_e32 v81, 0xbfb8aa3b, v77
	v_exp_f32_e32 v74, v74
	v_exp_f32_e32 v75, v75
	v_exp_f32_e32 v80, v80
	v_exp_f32_e32 v81, v81
	v_add_f32_e32 v69, 1.0, v69
	v_add_f32_e32 v71, 1.0, v71
	v_add_f32_e32 v78, 1.0, v78
	v_add_f32_e32 v79, 1.0, v79
	v_add_f32_e32 v74, 1.0, v74
	v_add_f32_e32 v75, 1.0, v75
	v_rcp_f32_e32 v69, v69
	v_rcp_f32_e32 v71, v71
	v_rcp_f32_e32 v78, v78
	v_rcp_f32_e32 v79, v79
	v_add_f32_e32 v80, 1.0, v80
	v_add_f32_e32 v81, 1.0, v81
	v_rcp_f32_e32 v74, v74
	v_rcp_f32_e32 v75, v75
	v_rcp_f32_e32 v80, v80
	v_rcp_f32_e32 v81, v81
	v_mul_f32_e32 v68, v68, v69
	v_mul_f32_e32 v69, v70, v71
	v_mul_f32_e32 v70, v72, v78
	v_mul_f32_e32 v71, v73, v79
	v_mul_f32_e32 v72, v66, v74
	v_mul_f32_e32 v73, v67, v75
	v_cvt_pkrtz_f16_f32 v66, v68, v69
	v_cvt_pkrtz_f16_f32 v67, v70, v71
	v_mul_f32_e32 v69, v76, v86
	v_mul_f32_e32 v70, v77, v87
	v_mul_f32_e32 v69, v69, v80
	v_mul_f32_e32 v70, v70, v81
	v_cvt_pkrtz_f16_f32 v68, v72, v73
	v_cvt_pkrtz_f16_f32 v69, v69, v70
	global_store_dwordx4 v[82:83], v[66:69], off
	s_nop 1
	v_mov_b32_e32 v66, v195
	v_add_u32_e32 v67, 0x80, v146
	v_mad_i64_i32 v[68:69], s[8:9], v67, s58, v[114:115]
	v_lshl_add_u64 v[68:69], v[68:69], 0, v[116:117]
	v_pk_mul_f32 v[64:65], v[64:65], v[66:67] op_sel_hi:[1,0]
	v_pk_mul_f32 v[62:63], v[62:63], v[66:67] op_sel_hi:[1,0]
	v_pk_mul_f32 v[60:61], v[60:61], v[66:67] op_sel_hi:[1,0]
	v_pk_mul_f32 v[58:59], v[58:59], v[66:67] op_sel_hi:[1,0]
	v_pk_mul_f32 v[56:57], v[56:57], v[66:67] op_sel_hi:[1,0]
	v_pk_mul_f32 v[54:55], v[54:55], v[66:67] op_sel_hi:[1,0]
	v_pk_mul_f32 v[52:53], v[52:53], v[66:67] op_sel_hi:[1,0]
	v_pk_mul_f32 v[50:51], v[50:51], v[66:67] op_sel_hi:[1,0]
	v_mul_f32_e32 v54, v62, v54
	v_mul_f32_e32 v62, 0xbfb8aa3b, v62
	v_mul_f32_e32 v55, v63, v55
	v_mul_f32_e32 v63, 0xbfb8aa3b, v63
	v_mul_f32_e32 v56, v64, v56
	v_mul_f32_e32 v64, 0xbfb8aa3b, v64
	v_mul_f32_e32 v57, v65, v57
	v_mul_f32_e32 v65, 0xbfb8aa3b, v65
	v_mul_f32_e32 v50, v58, v50
	v_mul_f32_e32 v58, 0xbfb8aa3b, v58
	v_mul_f32_e32 v51, v59, v51
	v_mul_f32_e32 v59, 0xbfb8aa3b, v59
	v_mul_f32_e32 v52, v60, v52
	v_mul_f32_e32 v60, 0xbfb8aa3b, v60
	v_mul_f32_e32 v53, v61, v53
	v_mul_f32_e32 v61, 0xbfb8aa3b, v61
	v_exp_f32_e32 v62, v62
	v_exp_f32_e32 v63, v63
	v_exp_f32_e32 v64, v64
	v_exp_f32_e32 v65, v65
	v_exp_f32_e32 v58, v58
	v_exp_f32_e32 v59, v59
	v_exp_f32_e32 v60, v60
	v_exp_f32_e32 v61, v61
	v_add_f32_e32 v62, 1.0, v62
	v_add_f32_e32 v63, 1.0, v63
	v_add_f32_e32 v64, 1.0, v64
	v_add_f32_e32 v65, 1.0, v65
	v_add_f32_e32 v58, 1.0, v58
	v_add_f32_e32 v59, 1.0, v59
	v_add_f32_e32 v60, 1.0, v60
	v_add_f32_e32 v61, 1.0, v61
	v_rcp_f32_e32 v62, v62
	v_rcp_f32_e32 v63, v63
	v_rcp_f32_e32 v64, v64
	v_rcp_f32_e32 v65, v65
	v_rcp_f32_e32 v58, v58
	v_rcp_f32_e32 v59, v59
	v_rcp_f32_e32 v60, v60
	v_rcp_f32_e32 v61, v61
	v_mul_f32_e32 v54, v54, v62
	v_mul_f32_e32 v55, v55, v63
	v_mul_f32_e32 v56, v56, v64
	v_mul_f32_e32 v57, v57, v65
	v_mul_f32_e32 v58, v50, v58
	v_mul_f32_e32 v59, v51, v59
	v_mul_f32_e32 v60, v52, v60
	v_mul_f32_e32 v53, v53, v61
	v_cvt_pkrtz_f16_f32 v50, v54, v55
	v_cvt_pkrtz_f16_f32 v51, v56, v57
	v_cvt_pkrtz_f16_f32 v52, v58, v59
	v_cvt_pkrtz_f16_f32 v53, v60, v53
	global_store_dwordx4 v[68:69], v[50:53], off
	s_nop 1
	v_mov_b32_e32 v50, v196
	v_add_u32_e32 v51, 0x90, v146
	v_mad_i64_i32 v[52:53], s[8:9], v51, s58, v[114:115]
	v_lshl_add_u64 v[52:53], v[52:53], 0, v[116:117]
	v_pk_mul_f32 v[48:49], v[48:49], v[50:51] op_sel_hi:[1,0]
	v_pk_mul_f32 v[46:47], v[46:47], v[50:51] op_sel_hi:[1,0]
	v_pk_mul_f32 v[44:45], v[44:45], v[50:51] op_sel_hi:[1,0]
	v_pk_mul_f32 v[42:43], v[42:43], v[50:51] op_sel_hi:[1,0]
	v_pk_mul_f32 v[40:41], v[40:41], v[50:51] op_sel_hi:[1,0]
	v_pk_mul_f32 v[38:39], v[38:39], v[50:51] op_sel_hi:[1,0]
	v_pk_mul_f32 v[36:37], v[36:37], v[50:51] op_sel_hi:[1,0]
	v_pk_mul_f32 v[34:35], v[34:35], v[50:51] op_sel_hi:[1,0]
	v_mul_f32_e32 v38, v46, v38
	v_mul_f32_e32 v46, 0xbfb8aa3b, v46
	v_mul_f32_e32 v39, v47, v39
	v_mul_f32_e32 v47, 0xbfb8aa3b, v47
	v_mul_f32_e32 v40, v48, v40
	v_mul_f32_e32 v48, 0xbfb8aa3b, v48
	v_mul_f32_e32 v41, v49, v41
	v_mul_f32_e32 v49, 0xbfb8aa3b, v49
	v_mul_f32_e32 v34, v42, v34
	v_mul_f32_e32 v42, 0xbfb8aa3b, v42
	v_mul_f32_e32 v35, v43, v35
	v_mul_f32_e32 v43, 0xbfb8aa3b, v43
	v_mul_f32_e32 v36, v44, v36
	v_mul_f32_e32 v44, 0xbfb8aa3b, v44
	v_mul_f32_e32 v37, v45, v37
	v_mul_f32_e32 v45, 0xbfb8aa3b, v45
	v_exp_f32_e32 v46, v46
	v_exp_f32_e32 v47, v47
	v_exp_f32_e32 v48, v48
	v_exp_f32_e32 v49, v49
	v_exp_f32_e32 v42, v42
	v_exp_f32_e32 v43, v43
	v_exp_f32_e32 v44, v44
	v_exp_f32_e32 v45, v45
	v_add_f32_e32 v46, 1.0, v46
	v_add_f32_e32 v47, 1.0, v47
	v_add_f32_e32 v48, 1.0, v48
	v_add_f32_e32 v49, 1.0, v49
	v_add_f32_e32 v42, 1.0, v42
	v_add_f32_e32 v43, 1.0, v43
	v_add_f32_e32 v44, 1.0, v44
	v_add_f32_e32 v45, 1.0, v45
	v_rcp_f32_e32 v46, v46
	v_rcp_f32_e32 v47, v47
	v_rcp_f32_e32 v48, v48
	v_rcp_f32_e32 v49, v49
	v_rcp_f32_e32 v42, v42
	v_rcp_f32_e32 v43, v43
	v_rcp_f32_e32 v44, v44
	v_rcp_f32_e32 v45, v45
	v_mul_f32_e32 v38, v38, v46
	v_mul_f32_e32 v39, v39, v47
	v_mul_f32_e32 v40, v40, v48
	v_mul_f32_e32 v41, v41, v49
	v_mul_f32_e32 v42, v34, v42
	v_mul_f32_e32 v43, v35, v43
	v_mul_f32_e32 v44, v36, v44
	v_mul_f32_e32 v37, v37, v45
	v_cvt_pkrtz_f16_f32 v34, v38, v39
	v_cvt_pkrtz_f16_f32 v35, v40, v41
	v_cvt_pkrtz_f16_f32 v36, v42, v43
	v_cvt_pkrtz_f16_f32 v37, v44, v37
	global_store_dwordx4 v[52:53], v[34:37], off
	s_nop 1
	v_mov_b32_e32 v34, v197
	v_add_u32_e32 v35, 0xa0, v146
	v_mad_i64_i32 v[36:37], s[8:9], v35, s58, v[114:115]
	v_lshl_add_u64 v[36:37], v[36:37], 0, v[116:117]
	v_pk_mul_f32 v[32:33], v[32:33], v[34:35] op_sel_hi:[1,0]
	v_pk_mul_f32 v[30:31], v[30:31], v[34:35] op_sel_hi:[1,0]
	v_pk_mul_f32 v[28:29], v[28:29], v[34:35] op_sel_hi:[1,0]
	v_pk_mul_f32 v[26:27], v[26:27], v[34:35] op_sel_hi:[1,0]
	v_pk_mul_f32 v[24:25], v[24:25], v[34:35] op_sel_hi:[1,0]
	v_pk_mul_f32 v[22:23], v[22:23], v[34:35] op_sel_hi:[1,0]
	v_pk_mul_f32 v[20:21], v[20:21], v[34:35] op_sel_hi:[1,0]
	v_pk_mul_f32 v[18:19], v[18:19], v[34:35] op_sel_hi:[1,0]
	v_mul_f32_e32 v22, v30, v22
	v_mul_f32_e32 v30, 0xbfb8aa3b, v30
	v_mul_f32_e32 v23, v31, v23
	v_mul_f32_e32 v31, 0xbfb8aa3b, v31
	v_mul_f32_e32 v24, v32, v24
	v_mul_f32_e32 v32, 0xbfb8aa3b, v32
	v_mul_f32_e32 v25, v33, v25
	v_mul_f32_e32 v33, 0xbfb8aa3b, v33
	v_mul_f32_e32 v18, v26, v18
	v_mul_f32_e32 v26, 0xbfb8aa3b, v26
	v_mul_f32_e32 v19, v27, v19
	v_mul_f32_e32 v27, 0xbfb8aa3b, v27
	v_mul_f32_e32 v20, v28, v20
	v_mul_f32_e32 v28, 0xbfb8aa3b, v28
	v_mul_f32_e32 v21, v29, v21
	v_mul_f32_e32 v29, 0xbfb8aa3b, v29
	v_exp_f32_e32 v30, v30
	v_exp_f32_e32 v31, v31
	v_exp_f32_e32 v32, v32
	v_exp_f32_e32 v33, v33
	v_exp_f32_e32 v26, v26
	v_exp_f32_e32 v27, v27
	v_exp_f32_e32 v28, v28
	v_exp_f32_e32 v29, v29
	v_add_f32_e32 v30, 1.0, v30
	v_add_f32_e32 v31, 1.0, v31
	v_add_f32_e32 v32, 1.0, v32
	v_add_f32_e32 v33, 1.0, v33
	v_add_f32_e32 v26, 1.0, v26
	v_add_f32_e32 v27, 1.0, v27
	v_add_f32_e32 v28, 1.0, v28
	v_add_f32_e32 v29, 1.0, v29
	v_rcp_f32_e32 v30, v30
	v_rcp_f32_e32 v31, v31
	v_rcp_f32_e32 v32, v32
	v_rcp_f32_e32 v33, v33
	v_rcp_f32_e32 v26, v26
	v_rcp_f32_e32 v27, v27
	v_rcp_f32_e32 v28, v28
	v_rcp_f32_e32 v29, v29
	v_mul_f32_e32 v22, v22, v30
	v_mul_f32_e32 v23, v23, v31
	v_mul_f32_e32 v24, v24, v32
	v_mul_f32_e32 v25, v25, v33
	v_mul_f32_e32 v26, v18, v26
	v_mul_f32_e32 v27, v19, v27
	v_mul_f32_e32 v28, v20, v28
	v_mul_f32_e32 v21, v21, v29
	v_cvt_pkrtz_f16_f32 v18, v22, v23
	v_cvt_pkrtz_f16_f32 v19, v24, v25
	v_cvt_pkrtz_f16_f32 v20, v26, v27
	v_cvt_pkrtz_f16_f32 v21, v28, v21
	global_store_dwordx4 v[36:37], v[18:21], off
	s_nop 1
	v_mov_b32_e32 v18, v198
	v_add_u32_e32 v19, 0xb0, v146
	v_mad_i64_i32 v[20:21], s[8:9], v19, s58, v[114:115]
	v_lshl_add_u64 v[20:21], v[20:21], 0, v[116:117]
	v_pk_mul_f32 v[16:17], v[16:17], v[18:19] op_sel_hi:[1,0]
	v_pk_mul_f32 v[14:15], v[14:15], v[18:19] op_sel_hi:[1,0]
	v_pk_mul_f32 v[12:13], v[12:13], v[18:19] op_sel_hi:[1,0]
	v_pk_mul_f32 v[10:11], v[10:11], v[18:19] op_sel_hi:[1,0]
	v_pk_mul_f32 v[8:9], v[8:9], v[18:19] op_sel_hi:[1,0]
	v_pk_mul_f32 v[6:7], v[6:7], v[18:19] op_sel_hi:[1,0]
	v_pk_mul_f32 v[4:5], v[4:5], v[18:19] op_sel_hi:[1,0]
	v_pk_mul_f32 v[2:3], v[2:3], v[18:19] op_sel_hi:[1,0]
	v_mul_f32_e32 v6, v14, v6
	v_mul_f32_e32 v14, 0xbfb8aa3b, v14
	v_mul_f32_e32 v7, v15, v7
	v_mul_f32_e32 v15, 0xbfb8aa3b, v15
	v_mul_f32_e32 v8, v16, v8
	v_mul_f32_e32 v16, 0xbfb8aa3b, v16
	v_mul_f32_e32 v9, v17, v9
	v_mul_f32_e32 v17, 0xbfb8aa3b, v17
	v_mul_f32_e32 v2, v10, v2
	v_mul_f32_e32 v10, 0xbfb8aa3b, v10
	v_mul_f32_e32 v3, v11, v3
	v_mul_f32_e32 v11, 0xbfb8aa3b, v11
	v_mul_f32_e32 v4, v12, v4
	v_mul_f32_e32 v12, 0xbfb8aa3b, v12
	v_mul_f32_e32 v5, v13, v5
	v_mul_f32_e32 v13, 0xbfb8aa3b, v13
	v_exp_f32_e32 v14, v14
	v_exp_f32_e32 v15, v15
	v_exp_f32_e32 v16, v16
	v_exp_f32_e32 v17, v17
	v_exp_f32_e32 v10, v10
	v_exp_f32_e32 v11, v11
	v_exp_f32_e32 v12, v12
	v_exp_f32_e32 v13, v13
	v_add_f32_e32 v14, 1.0, v14
	v_add_f32_e32 v15, 1.0, v15
	v_add_f32_e32 v16, 1.0, v16
	v_add_f32_e32 v17, 1.0, v17
	v_add_f32_e32 v10, 1.0, v10
	v_add_f32_e32 v11, 1.0, v11
	v_add_f32_e32 v12, 1.0, v12
	v_add_f32_e32 v13, 1.0, v13
	v_rcp_f32_e32 v14, v14
	v_rcp_f32_e32 v15, v15
	v_rcp_f32_e32 v16, v16
	v_rcp_f32_e32 v17, v17
	v_rcp_f32_e32 v10, v10
	v_rcp_f32_e32 v11, v11
	v_rcp_f32_e32 v12, v12
	v_rcp_f32_e32 v13, v13
	v_mul_f32_e32 v6, v6, v14
	v_mul_f32_e32 v7, v7, v15
	v_mul_f32_e32 v8, v8, v16
	v_mul_f32_e32 v9, v9, v17
	v_mul_f32_e32 v10, v2, v10
	v_mul_f32_e32 v11, v3, v11
	v_mul_f32_e32 v12, v4, v12
	v_mul_f32_e32 v5, v5, v13
	v_cvt_pkrtz_f16_f32 v2, v6, v7
	v_cvt_pkrtz_f16_f32 v3, v8, v9
	v_cvt_pkrtz_f16_f32 v4, v10, v11
	v_cvt_pkrtz_f16_f32 v5, v12, v5
	global_store_dwordx4 v[20:21], v[2:5], off
	s_cbranch_vccnz .LBB0_1011
	s_andn2_b64 vcc, exec, s[0:1]
	s_cbranch_vccnz .LBB0_1010
	s_barrier
	s_branch .LBB0_1010

.LBB0_1166:
	ds_read_b128 v[104:107], v167
	ds_read_b128 v[108:111], v167 offset:1024
	ds_read_b128 v[112:115], v167 offset:2048
	ds_read_b128 v[120:123], v167 offset:3072
	ds_read_b128 v[158:161], v168
	ds_read_b128 v[170:173], v168 offset:1024
	ds_read_b128 v[174:177], v168 offset:2048
	ds_read_b128 v[178:181], v168 offset:3072
	s_add_u32 s26, s6, 0xffea8080
	s_addc_u32 s27, s7, -1
	s_cmpk_eq_i32 s55, 0x52
	s_cselect_b32 s29, s23, s27
	s_cselect_b32 s28, s22, s26
	s_cselect_b32 s27, s25, s9
	s_cselect_b32 s26, s24, s8
	v_lshl_add_u64 v[214:215], s[6:7], 0, v[152:153]
	s_add_i32 m0, s38, 0xc000
	ds_read_b128 v[182:185], v169
	ds_read_b128 v[186:189], v169 offset:1024
	ds_read_b128 v[190:193], v169 offset:2048
	ds_read_b128 v[194:197], v169 offset:3072
	ds_read_b128 v[198:201], v169 offset:4096
	ds_read_b128 v[202:205], v169 offset:5120
	ds_read_b128 v[206:209], v169 offset:6144
	ds_read_b128 v[210:213], v169 offset:7168
	global_load_lds_dwordx4 v[214:215], off
	v_lshl_add_u64 v[214:215], s[6:7], 0, v[154:155]
	s_add_i32 m0, s38, 0xe000
	s_nop 0
	global_load_lds_dwordx4 v[214:215], off
	s_waitcnt vmcnt(8)
	s_waitcnt lgkmcnt(0)
	s_barrier
	s_setprio 1
	s_waitcnt lgkmcnt(0)
	v_mfma_i32_16x16x64_i8 v[140:143], v[104:107], v[182:185], v[140:143]
	v_mfma_i32_16x16x64_i8 v[136:139], v[112:115], v[182:185], v[136:139]
	v_mfma_i32_16x16x64_i8 v[124:127], v[104:107], v[190:193], v[124:127]
	v_mfma_i32_16x16x64_i8 v[116:119], v[112:115], v[190:193], v[116:119]
	v_mfma_i32_16x16x64_i8 v[92:95], v[104:107], v[198:201], v[92:95]
	v_mfma_i32_16x16x64_i8 v[88:91], v[112:115], v[198:201], v[88:91]
	v_mfma_i32_16x16x64_i8 v[76:79], v[104:107], v[206:209], v[76:79]
	v_mfma_i32_16x16x64_i8 v[72:75], v[112:115], v[206:209], v[72:75]
	v_mfma_i32_16x16x64_i8 v[140:143], v[108:111], v[186:189], v[140:143]
	v_mfma_i32_16x16x64_i8 v[136:139], v[120:123], v[186:189], v[136:139]
	v_mfma_i32_16x16x64_i8 v[124:127], v[108:111], v[194:197], v[124:127]
	v_mfma_i32_16x16x64_i8 v[116:119], v[120:123], v[194:197], v[116:119]
	v_mfma_i32_16x16x64_i8 v[92:95], v[108:111], v[202:205], v[92:95]
	v_mfma_i32_16x16x64_i8 v[88:91], v[120:123], v[202:205], v[88:91]
	v_mfma_i32_16x16x64_i8 v[76:79], v[108:111], v[210:213], v[76:79]
	v_mfma_i32_16x16x64_i8 v[72:75], v[120:123], v[210:213], v[72:75]
	s_setprio 0
	s_setprio 1
	v_mfma_i32_16x16x64_i8 v[132:135], v[158:161], v[182:185], v[132:135]
	v_mfma_i32_16x16x64_i8 v[128:131], v[174:177], v[182:185], v[128:131]
	v_mfma_i32_16x16x64_i8 v[100:103], v[158:161], v[190:193], v[100:103]
	v_mfma_i32_16x16x64_i8 v[96:99], v[174:177], v[190:193], v[96:99]
	v_mfma_i32_16x16x64_i8 v[84:87], v[158:161], v[198:201], v[84:87]
	v_mfma_i32_16x16x64_i8 v[80:83], v[174:177], v[198:201], v[80:83]
	v_mfma_i32_16x16x64_i8 v[68:71], v[158:161], v[206:209], v[68:71]
	v_mfma_i32_16x16x64_i8 v[64:67], v[174:177], v[206:209], v[64:67]
	v_mfma_i32_16x16x64_i8 v[132:135], v[170:173], v[186:189], v[132:135]
	v_mfma_i32_16x16x64_i8 v[128:131], v[178:181], v[186:189], v[128:131]
	v_mfma_i32_16x16x64_i8 v[100:103], v[170:173], v[194:197], v[100:103]
	v_mfma_i32_16x16x64_i8 v[96:99], v[178:181], v[194:197], v[96:99]
	v_mfma_i32_16x16x64_i8 v[84:87], v[170:173], v[202:205], v[84:87]
	v_mfma_i32_16x16x64_i8 v[80:83], v[178:181], v[202:205], v[80:83]
	v_mfma_i32_16x16x64_i8 v[68:71], v[170:173], v[210:213], v[68:71]
	v_mfma_i32_16x16x64_i8 v[64:67], v[178:181], v[210:213], v[64:67]
	s_setprio 0
	s_barrier
	s_add_i32 s56, s48, s35
	v_lshl_add_u64 v[214:215], s[26:27], 0, v[146:147]
	s_mov_b32 m0, s56
	ds_read_b128 v[182:185], v169 offset:16384
	ds_read_b128 v[186:189], v169 offset:17408
	ds_read_b128 v[190:193], v169 offset:18432
	ds_read_b128 v[194:197], v169 offset:19456
	ds_read_b128 v[198:201], v169 offset:20480
	ds_read_b128 v[202:205], v169 offset:21504
	ds_read_b128 v[206:209], v169 offset:22528
	ds_read_b128 v[210:213], v169 offset:23552
	global_load_lds_dwordx4 v[214:215], off
	s_add_i32 m0, s56, 0x2000
	s_add_u32 s56, s26, 0x158000
	v_lshl_add_u64 v[216:217], s[26:27], 0, v[150:151]
	s_addc_u32 s57, s27, 0
	s_add_i32 s58, s49, s35
	global_load_lds_dwordx4 v[216:217], off
	v_lshl_add_u64 v[218:219], s[56:57], 0, v[146:147]
	s_mov_b32 m0, s58
	v_lshl_add_u64 v[220:221], s[28:29], 0, v[148:149]
	global_load_lds_dwordx4 v[218:219], off
	v_lshl_add_u64 v[218:219], s[56:57], 0, v[150:151]
	s_add_i32 m0, s58, 0x2000
	s_nop 0
	global_load_lds_dwordx4 v[218:219], off
	v_lshl_add_u64 v[218:219], s[28:29], 0, v[144:145]
	s_mov_b32 m0, s38
	s_nop 0
	global_load_lds_dwordx4 v[218:219], off
	s_mov_b32 m0, s39
	s_nop 0
	global_load_lds_dwordx4 v[220:221], off
	s_waitcnt vmcnt(8)
	s_waitcnt lgkmcnt(0)
	s_barrier
	s_setprio 1
	s_waitcnt lgkmcnt(0)
	v_mfma_i32_16x16x64_i8 v[60:63], v[104:107], v[182:185], v[60:63]
	v_mfma_i32_16x16x64_i8 v[56:59], v[112:115], v[182:185], v[56:59]
	v_mfma_i32_16x16x64_i8 v[44:47], v[104:107], v[190:193], v[44:47]
	v_mfma_i32_16x16x64_i8 v[40:43], v[112:115], v[190:193], v[40:43]
	v_mfma_i32_16x16x64_i8 v[28:31], v[104:107], v[198:201], v[28:31]
	v_mfma_i32_16x16x64_i8 v[24:27], v[112:115], v[198:201], v[24:27]
	v_mfma_i32_16x16x64_i8 v[12:15], v[104:107], v[206:209], v[12:15]
	v_mfma_i32_16x16x64_i8 v[8:11], v[112:115], v[206:209], v[8:11]
	v_mfma_i32_16x16x64_i8 v[60:63], v[108:111], v[186:189], v[60:63]
	v_mfma_i32_16x16x64_i8 v[56:59], v[120:123], v[186:189], v[56:59]
	v_mfma_i32_16x16x64_i8 v[44:47], v[108:111], v[194:197], v[44:47]
	v_mfma_i32_16x16x64_i8 v[40:43], v[120:123], v[194:197], v[40:43]
	v_mfma_i32_16x16x64_i8 v[28:31], v[108:111], v[202:205], v[28:31]
	v_mfma_i32_16x16x64_i8 v[24:27], v[120:123], v[202:205], v[24:27]
	v_mfma_i32_16x16x64_i8 v[12:15], v[108:111], v[210:213], v[12:15]
	v_mfma_i32_16x16x64_i8 v[8:11], v[120:123], v[210:213], v[8:11]
	s_setprio 0
	s_setprio 1
	v_mfma_i32_16x16x64_i8 v[52:55], v[158:161], v[182:185], v[52:55]
	v_mfma_i32_16x16x64_i8 v[48:51], v[174:177], v[182:185], v[48:51]
	v_mfma_i32_16x16x64_i8 v[36:39], v[158:161], v[190:193], v[36:39]
	v_mfma_i32_16x16x64_i8 v[32:35], v[174:177], v[190:193], v[32:35]
	v_mfma_i32_16x16x64_i8 v[20:23], v[158:161], v[198:201], v[20:23]
	v_mfma_i32_16x16x64_i8 v[16:19], v[174:177], v[198:201], v[16:19]
	v_mfma_i32_16x16x64_i8 v[4:7], v[158:161], v[206:209], v[4:7]
	v_mfma_i32_16x16x64_i8 v[0:3], v[174:177], v[206:209], v[0:3]
	v_mfma_i32_16x16x64_i8 v[52:55], v[170:173], v[186:189], v[52:55]
	v_mfma_i32_16x16x64_i8 v[48:51], v[178:181], v[186:189], v[48:51]
	v_mfma_i32_16x16x64_i8 v[36:39], v[170:173], v[194:197], v[36:39]
	v_mfma_i32_16x16x64_i8 v[32:35], v[178:181], v[194:197], v[32:35]
	v_mfma_i32_16x16x64_i8 v[20:23], v[170:173], v[202:205], v[20:23]
	v_mfma_i32_16x16x64_i8 v[16:19], v[178:181], v[202:205], v[16:19]
	v_mfma_i32_16x16x64_i8 v[4:7], v[170:173], v[210:213], v[4:7]
	v_mfma_i32_16x16x64_i8 v[0:3], v[178:181], v[210:213], v[0:3]
	s_setprio 0
	s_barrier
	s_add_i32 s56, 0, 0x18000
	s_add_i32 s57, 0, 0x1c000
	v_add_u32_e32 v120, s56, v165
	v_add_u32_e32 v162, s57, v165
	ds_read_b128 v[104:107], v120
	ds_read_b128 v[108:111], v120 offset:1024
	ds_read_b128 v[112:115], v120 offset:2048
	ds_read_b128 v[120:123], v120 offset:3072
	ds_read_b128 v[158:161], v162
	ds_read_b128 v[170:173], v162 offset:1024
	ds_read_b128 v[174:177], v162 offset:2048
	ds_read_b128 v[178:181], v162 offset:3072
	s_add_u32 s28, s28, 0x158000
	s_addc_u32 s29, s29, 0
	s_mov_b32 m0, s40
	v_lshl_add_u64 v[222:223], s[28:29], 0, v[144:145]
	ds_read_b128 v[182:185], v169 offset:32768
	ds_read_b128 v[186:189], v169 offset:33792
	ds_read_b128 v[190:193], v169 offset:34816
	ds_read_b128 v[194:197], v169 offset:35840
	ds_read_b128 v[198:201], v169 offset:36864
	ds_read_b128 v[202:205], v169 offset:37888
	ds_read_b128 v[206:209], v169 offset:38912
	ds_read_b128 v[210:213], v169 offset:39936
	global_load_lds_dwordx4 v[222:223], off
	v_lshl_add_u64 v[222:223], s[28:29], 0, v[148:149]
	s_mov_b32 m0, s41
	s_nop 0
	global_load_lds_dwordx4 v[222:223], off
	s_waitcnt vmcnt(8)
	s_waitcnt lgkmcnt(0)
	s_barrier
	s_setprio 1
	s_waitcnt lgkmcnt(0)
	v_mfma_i32_16x16x64_i8 v[140:143], v[104:107], v[182:185], v[140:143]
	v_mfma_i32_16x16x64_i8 v[136:139], v[112:115], v[182:185], v[136:139]
	v_mfma_i32_16x16x64_i8 v[124:127], v[104:107], v[190:193], v[124:127]
	v_mfma_i32_16x16x64_i8 v[116:119], v[112:115], v[190:193], v[116:119]
	v_mfma_i32_16x16x64_i8 v[92:95], v[104:107], v[198:201], v[92:95]
	v_mfma_i32_16x16x64_i8 v[88:91], v[112:115], v[198:201], v[88:91]
	v_mfma_i32_16x16x64_i8 v[76:79], v[104:107], v[206:209], v[76:79]
	v_mfma_i32_16x16x64_i8 v[72:75], v[112:115], v[206:209], v[72:75]
	v_mfma_i32_16x16x64_i8 v[140:143], v[108:111], v[186:189], v[140:143]
	v_mfma_i32_16x16x64_i8 v[136:139], v[120:123], v[186:189], v[136:139]
	v_mfma_i32_16x16x64_i8 v[124:127], v[108:111], v[194:197], v[124:127]
	v_mfma_i32_16x16x64_i8 v[116:119], v[120:123], v[194:197], v[116:119]
	v_mfma_i32_16x16x64_i8 v[92:95], v[108:111], v[202:205], v[92:95]
	v_mfma_i32_16x16x64_i8 v[88:91], v[120:123], v[202:205], v[88:91]
	v_mfma_i32_16x16x64_i8 v[76:79], v[108:111], v[210:213], v[76:79]
	v_mfma_i32_16x16x64_i8 v[72:75], v[120:123], v[210:213], v[72:75]
	s_setprio 0
	s_setprio 1
	v_mfma_i32_16x16x64_i8 v[132:135], v[158:161], v[182:185], v[132:135]
	v_mfma_i32_16x16x64_i8 v[128:131], v[174:177], v[182:185], v[128:131]
	v_mfma_i32_16x16x64_i8 v[100:103], v[158:161], v[190:193], v[100:103]
	v_mfma_i32_16x16x64_i8 v[96:99], v[174:177], v[190:193], v[96:99]
	v_mfma_i32_16x16x64_i8 v[84:87], v[158:161], v[198:201], v[84:87]
	v_mfma_i32_16x16x64_i8 v[80:83], v[174:177], v[198:201], v[80:83]
	v_mfma_i32_16x16x64_i8 v[68:71], v[158:161], v[206:209], v[68:71]
	v_mfma_i32_16x16x64_i8 v[64:67], v[174:177], v[206:209], v[64:67]
	v_mfma_i32_16x16x64_i8 v[132:135], v[170:173], v[186:189], v[132:135]
	v_mfma_i32_16x16x64_i8 v[128:131], v[178:181], v[186:189], v[128:131]
	v_mfma_i32_16x16x64_i8 v[100:103], v[170:173], v[194:197], v[100:103]
	v_mfma_i32_16x16x64_i8 v[96:99], v[178:181], v[194:197], v[96:99]
	v_mfma_i32_16x16x64_i8 v[84:87], v[170:173], v[202:205], v[84:87]
	v_mfma_i32_16x16x64_i8 v[80:83], v[178:181], v[202:205], v[80:83]
	v_mfma_i32_16x16x64_i8 v[68:71], v[170:173], v[210:213], v[68:71]
	v_mfma_i32_16x16x64_i8 v[64:67], v[178:181], v[210:213], v[64:67]
	s_setprio 0
	s_barrier
	s_add_i32 s28, s56, s35
	v_lshl_add_u64 v[214:215], v[214:215], 0, s[16:17]
	s_mov_b32 m0, s28
	ds_read_b128 v[182:185], v169 offset:49152
	ds_read_b128 v[186:189], v169 offset:50176
	ds_read_b128 v[190:193], v169 offset:51200
	ds_read_b128 v[194:197], v169 offset:52224
	ds_read_b128 v[198:201], v169 offset:53248
	ds_read_b128 v[202:205], v169 offset:54272
	ds_read_b128 v[206:209], v169 offset:55296
	ds_read_b128 v[210:213], v169 offset:56320
	global_load_lds_dwordx4 v[214:215], off
	s_add_i32 m0, s28, 0x2000
	s_add_u32 s26, s26, 0x158080
	v_lshl_add_u64 v[214:215], v[216:217], 0, s[16:17]
	s_addc_u32 s27, s27, 0
	s_add_i32 s28, s57, s35
	global_load_lds_dwordx4 v[214:215], off
	v_lshl_add_u64 v[214:215], s[26:27], 0, v[146:147]
	s_mov_b32 m0, s28
	s_nop 0
	global_load_lds_dwordx4 v[214:215], off
	v_lshl_add_u64 v[214:215], s[26:27], 0, v[150:151]
	s_add_i32 m0, s28, 0x2000
	s_nop 0
	global_load_lds_dwordx4 v[214:215], off
	v_lshl_add_u64 v[214:215], v[218:219], 0, s[16:17]
	s_mov_b32 m0, s42
	s_nop 0
	global_load_lds_dwordx4 v[214:215], off
	v_lshl_add_u64 v[214:215], v[220:221], 0, s[16:17]
	s_mov_b32 m0, s43
	s_nop 0
	global_load_lds_dwordx4 v[214:215], off
	s_waitcnt vmcnt(8)
	s_waitcnt lgkmcnt(0)
	s_barrier
	s_setprio 1
	s_waitcnt lgkmcnt(0)
	v_mfma_i32_16x16x64_i8 v[60:63], v[104:107], v[182:185], v[60:63]
	v_mfma_i32_16x16x64_i8 v[56:59], v[112:115], v[182:185], v[56:59]
	v_mfma_i32_16x16x64_i8 v[44:47], v[104:107], v[190:193], v[44:47]
	v_mfma_i32_16x16x64_i8 v[40:43], v[112:115], v[190:193], v[40:43]
	v_mfma_i32_16x16x64_i8 v[28:31], v[104:107], v[198:201], v[28:31]
	v_mfma_i32_16x16x64_i8 v[24:27], v[112:115], v[198:201], v[24:27]
	v_mfma_i32_16x16x64_i8 v[12:15], v[104:107], v[206:209], v[12:15]
	v_mfma_i32_16x16x64_i8 v[8:11], v[112:115], v[206:209], v[8:11]
	v_mfma_i32_16x16x64_i8 v[60:63], v[108:111], v[186:189], v[60:63]
	v_mfma_i32_16x16x64_i8 v[56:59], v[120:123], v[186:189], v[56:59]
	v_mfma_i32_16x16x64_i8 v[44:47], v[108:111], v[194:197], v[44:47]
	v_mfma_i32_16x16x64_i8 v[40:43], v[120:123], v[194:197], v[40:43]
	v_mfma_i32_16x16x64_i8 v[28:31], v[108:111], v[202:205], v[28:31]
	v_mfma_i32_16x16x64_i8 v[24:27], v[120:123], v[202:205], v[24:27]
	v_mfma_i32_16x16x64_i8 v[12:15], v[108:111], v[210:213], v[12:15]
	v_mfma_i32_16x16x64_i8 v[8:11], v[120:123], v[210:213], v[8:11]
	s_setprio 0
	s_setprio 1
	v_mfma_i32_16x16x64_i8 v[52:55], v[158:161], v[182:185], v[52:55]
	v_mfma_i32_16x16x64_i8 v[48:51], v[174:177], v[182:185], v[48:51]
	v_mfma_i32_16x16x64_i8 v[36:39], v[158:161], v[190:193], v[36:39]
	v_mfma_i32_16x16x64_i8 v[32:35], v[174:177], v[190:193], v[32:35]
	v_mfma_i32_16x16x64_i8 v[20:23], v[158:161], v[198:201], v[20:23]
	v_mfma_i32_16x16x64_i8 v[16:19], v[174:177], v[198:201], v[16:19]
	v_mfma_i32_16x16x64_i8 v[4:7], v[158:161], v[206:209], v[4:7]
	v_mfma_i32_16x16x64_i8 v[0:3], v[174:177], v[206:209], v[0:3]
	v_mfma_i32_16x16x64_i8 v[52:55], v[170:173], v[186:189], v[52:55]
	v_mfma_i32_16x16x64_i8 v[48:51], v[178:181], v[186:189], v[48:51]
	v_mfma_i32_16x16x64_i8 v[36:39], v[170:173], v[194:197], v[36:39]
	v_mfma_i32_16x16x64_i8 v[32:35], v[178:181], v[194:197], v[32:35]
	v_mfma_i32_16x16x64_i8 v[20:23], v[170:173], v[202:205], v[20:23]
	v_mfma_i32_16x16x64_i8 v[16:19], v[178:181], v[202:205], v[16:19]
	v_mfma_i32_16x16x64_i8 v[4:7], v[170:173], v[210:213], v[4:7]
	v_mfma_i32_16x16x64_i8 v[0:3], v[178:181], v[210:213], v[0:3]
	s_setprio 0
	s_barrier
	s_add_i32 s55, s55, 2
	s_add_u32 s6, s6, 0x100
	s_addc_u32 s7, s7, 0
	s_add_u32 s8, s8, 0x100
	s_addc_u32 s9, s9, 0
	s_cmpk_gt_u32 s55, 0x53
	s_cbranch_scc0 .LBB0_1166
	s_and_b64 vcc, exec, s[18:19]
	s_cbranch_vccz .LBB0_1169
.LBB0_1169:
	v_lshl_or_b32 v158, s54, 8, v166
	v_ashrrev_i32_e32 v159, 31, v158
	v_lshl_add_u64 v[108:109], v[158:159], 2, s[12:13]
	global_load_dwordx4 v[112:115], v[108:109], off offset:16
	global_load_dwordx4 v[120:123], v[108:109], off
	global_load_dwordx4 v[104:107], v[108:109], off offset:528
	s_nop 0
	global_load_dwordx4 v[108:111], v[108:109], off offset:512
	v_lshl_add_u32 v160, s53, 8, v163
	v_cndmask_b32_e64 v164, 0, 1, s[20:21]
	v_ashrrev_i32_e32 v161, 31, v160
	v_mov_b32_e32 v162, 0x39010204
	v_cmp_ne_u32_e64 s[6:7], 1, v164
	s_andn2_b64 vcc, exec, s[20:21]
	v_mov_b32_e32 v164, 0x39010204
	s_cbranch_vccnz .LBB0_1171
	v_lshl_add_u64 v[170:171], v[160:161], 2, s[70:71]
	global_load_dword v164, v[170:171], off
	global_load_dword v200, v[170:171], off offset:64
	global_load_dword v201, v[170:171], off offset:128
	global_load_dword v202, v[170:171], off offset:192
	global_load_dword v203, v[170:171], off offset:512
	global_load_dword v204, v[170:171], off offset:576
	global_load_dword v205, v[170:171], off offset:640
	global_load_dword v206, v[170:171], off offset:704
	s_waitcnt vmcnt(0)
	v_mul_f32_e32 v164, 0x39010204, v164
.LBB0_1171:
	v_cvt_f32_i32_e32 v141, v141
	v_cvt_f32_i32_e32 v143, v143
	v_cvt_f32_i32_e32 v142, v142
	v_cvt_f32_i32_e32 v140, v140
	v_cvt_f32_i32_e32 v139, v139
	v_cvt_f32_i32_e32 v137, v137
	v_cvt_f32_i32_e32 v136, v136
	v_cvt_f32_i32_e32 v138, v138
	v_cvt_f32_i32_e32 v133, v133
	v_cvt_f32_i32_e32 v132, v132
	v_cvt_f32_i32_e32 v131, v131
	v_cvt_f32_i32_e32 v129, v129
	v_cvt_f32_i32_e32 v128, v128
	v_cvt_f32_i32_e32 v130, v130
	v_cvt_f32_i32_e32 v135, v135
	v_cvt_f32_i32_e32 v134, v134
	v_lshlrev_b64 v[170:171], 13, v[160:161]
	v_lshl_add_u64 v[170:171], s[36:37], 0, v[170:171]
	s_waitcnt vmcnt(0)
	s_and_b64 vcc, exec, s[18:19]
	s_cbranch_vccz .Lalign_p13
	s_barrier
.Lalign_p13:
	v_pk_mul_f32 v[142:143], v[122:123], v[142:143]
	v_pk_mul_f32 v[140:141], v[120:121], v[140:141]
	v_pk_mul_f32 v[136:137], v[112:113], v[136:137]
	v_pk_mul_f32 v[138:139], v[114:115], v[138:139]
	v_lshl_add_u64 v[170:171], v[158:159], 1, v[170:171]
	v_pk_mul_f32 v[142:143], v[142:143], v[164:165] op_sel_hi:[1,0]
	v_pk_mul_f32 v[140:141], v[140:141], v[164:165] op_sel_hi:[1,0]
	v_pk_mul_f32 v[172:173], v[138:139], v[164:165] op_sel_hi:[1,0]
	v_pk_mul_f32 v[138:139], v[136:137], v[164:165] op_sel_hi:[1,0]
	v_cvt_pk_bf16_f32 v136, v140, v141
	v_cvt_pk_bf16_f32 v137, v142, v143
	v_pk_mul_f32 v[132:133], v[108:109], v[132:133]
	v_pk_mul_f32 v[128:129], v[104:105], v[128:129]
	v_pk_mul_f32 v[130:131], v[106:107], v[130:131]
	v_cvt_pk_bf16_f32 v138, v138, v139
	v_cvt_pk_bf16_f32 v139, v172, v173
	global_store_dwordx4 v[170:171], v[136:139], off
	v_pk_mul_f32 v[134:135], v[110:111], v[134:135]
	v_pk_mul_f32 v[132:133], v[132:133], v[164:165] op_sel_hi:[1,0]
	v_pk_mul_f32 v[136:137], v[130:131], v[164:165] op_sel_hi:[1,0]
	v_pk_mul_f32 v[130:131], v[128:129], v[164:165] op_sel_hi:[1,0]
	v_cvt_pk_bf16_f32 v128, v132, v133
	v_pk_mul_f32 v[134:135], v[134:135], v[164:165] op_sel_hi:[1,0]
	s_and_b64 vcc, exec, s[6:7]
	v_cvt_pk_bf16_f32 v129, v134, v135
	v_cvt_pk_bf16_f32 v130, v130, v131
	v_cvt_pk_bf16_f32 v131, v136, v137
	global_store_dwordx4 v[170:171], v[128:131], off offset:256
	s_nop 1
	v_or_b32_e32 v128, 16, v160
	v_ashrrev_i32_e32 v129, 31, v128
	s_cbranch_vccnz .LBB0_1173
	v_mul_f32_e32 v162, 0x39010204, v200
